# gemm8 k-loops: s_setprio 1 for the MFMA/ds_read part of each half-step, s_setprio 0 for the staging part
# speedup vs baseline: 1.0623x; 1.0024x over previous
.LBB0_195:
	ds_read_b128 v[160:163], v196
	ds_read_b128 v[164:167], v198
	ds_read_b128 v[180:183], v198 offset:64
	ds_read_b128 v[168:171], v196 offset:64
	ds_read_b128 v[172:175], v198 offset:2304
	ds_read_b128 v[206:209], v198 offset:2368
	ds_read_b128 v[176:179], v198 offset:4608
	ds_read_b128 v[210:213], v198 offset:4672
	ds_read_b128 v[184:187], v198 offset:6912
	ds_read_b128 v[214:217], v198 offset:6976
	s_waitcnt lgkmcnt(8)
	v_mfma_f32_16x16x32_bf16 v[156:159], v[164:167], v[160:163], v[156:159]
	s_add_i32 s49, s49, 2
	s_add_u32 s50, s45, 0xffffff80
	s_addc_u32 s51, s48, -1
	s_waitcnt lgkmcnt(5)
	v_mfma_f32_16x16x32_bf16 v[152:155], v[172:175], v[160:163], v[152:155]
	s_add_u32 s56, s30, 0xffffff80
	s_addc_u32 s57, s31, -1
	s_cmp_gt_u32 s49, 13
	s_waitcnt lgkmcnt(3)
	v_mfma_f32_16x16x32_bf16 v[148:151], v[176:179], v[160:163], v[148:151]
	s_cselect_b64 s[4:5], -1, 0
	s_and_b64 vcc, s[4:5], exec
	s_cselect_b32 s5, s11, s51
	s_waitcnt lgkmcnt(1)
	v_mfma_f32_16x16x32_bf16 v[144:147], v[184:187], v[160:163], v[144:147]
	ds_read_b128 v[160:163], v196 offset:2304
	ds_read_b128 v[188:191], v196 offset:2368
	s_cselect_b32 s4, s10, s50
	s_cselect_b32 s51, s13, s57
	s_waitcnt lgkmcnt(1)
	v_mfma_f32_16x16x32_bf16 v[140:143], v[164:167], v[160:163], v[140:143]
	s_cselect_b32 s50, s12, s56
	s_cmp_gt_u32 s49, 12
	v_mfma_f32_16x16x32_bf16 v[136:139], v[172:175], v[160:163], v[136:139]
	v_mfma_f32_16x16x32_bf16 v[132:135], v[176:179], v[160:163], v[132:135]
	v_mfma_f32_16x16x32_bf16 v[128:131], v[184:187], v[160:163], v[128:131]
	ds_read_b128 v[160:163], v196 offset:4608
	ds_read_b128 v[218:221], v196 offset:4672
	s_waitcnt lgkmcnt(1)
	v_mfma_f32_16x16x32_bf16 v[124:127], v[164:167], v[160:163], v[124:127]
	v_mfma_f32_16x16x32_bf16 v[120:123], v[172:175], v[160:163], v[120:123]
	v_mfma_f32_16x16x32_bf16 v[116:119], v[176:179], v[160:163], v[116:119]
	v_mfma_f32_16x16x32_bf16 v[112:115], v[184:187], v[160:163], v[112:115]
	ds_read_b128 v[160:163], v196 offset:6912
	ds_read_b128 v[222:225], v196 offset:6976
	s_waitcnt lgkmcnt(1)
	v_mfma_f32_16x16x32_bf16 v[108:111], v[164:167], v[160:163], v[108:111]
	v_mfma_f32_16x16x32_bf16 v[104:107], v[172:175], v[160:163], v[104:107]
	v_mfma_f32_16x16x32_bf16 v[100:103], v[176:179], v[160:163], v[100:103]
	v_mfma_f32_16x16x32_bf16 v[96:99], v[184:187], v[160:163], v[96:99]
	ds_read_b128 v[160:163], v196 offset:9216
	ds_read_b128 v[226:229], v196 offset:9280
	s_waitcnt lgkmcnt(1)
	v_mfma_f32_16x16x32_bf16 v[92:95], v[164:167], v[160:163], v[92:95]
	v_mfma_f32_16x16x32_bf16 v[88:91], v[172:175], v[160:163], v[88:91]
	v_mfma_f32_16x16x32_bf16 v[84:87], v[176:179], v[160:163], v[84:87]
	v_mfma_f32_16x16x32_bf16 v[80:83], v[184:187], v[160:163], v[80:83]
	ds_read_b128 v[160:163], v196 offset:11520
	ds_read_b128 v[230:233], v196 offset:11584
	s_waitcnt lgkmcnt(1)
	v_mfma_f32_16x16x32_bf16 v[68:71], v[164:167], v[160:163], v[68:71]
	v_mfma_f32_16x16x32_bf16 v[64:67], v[172:175], v[160:163], v[64:67]
	v_mfma_f32_16x16x32_bf16 v[60:63], v[176:179], v[160:163], v[60:63]
	v_mfma_f32_16x16x32_bf16 v[56:59], v[184:187], v[160:163], v[56:59]
	ds_read_b128 v[160:163], v196 offset:13824
	ds_read_b128 v[234:237], v196 offset:13888
	s_waitcnt lgkmcnt(1)
	v_mfma_f32_16x16x32_bf16 v[52:55], v[164:167], v[160:163], v[52:55]
	v_mfma_f32_16x16x32_bf16 v[48:51], v[172:175], v[160:163], v[48:51]
	v_mfma_f32_16x16x32_bf16 v[44:47], v[176:179], v[160:163], v[44:47]
	v_mfma_f32_16x16x32_bf16 v[40:43], v[184:187], v[160:163], v[40:43]
	ds_read_b128 v[160:163], v196 offset:16128
	ds_read_b128 v[238:241], v196 offset:16192
	s_setprio 0
	s_waitcnt vmcnt(6)
	ds_write_b128 v194, v[4:7] offset:36864
	s_waitcnt vmcnt(5)
	ds_write_b128 v194, v[8:11] offset:46080
	s_waitcnt vmcnt(4)
	ds_write_b128 v194, v[12:15] offset:55296
	s_waitcnt vmcnt(3)
	ds_write_b128 v194, v[16:19] offset:64512
	s_waitcnt vmcnt(3)
	ds_write_b128 v199, v[0:3]
	s_waitcnt vmcnt(2)
	ds_write_b128 v199, v[20:23] offset:9216
	v_mfma_f32_16x16x32_bf16 v[20:23], v[214:217], v[226:229], v[80:83]
	s_waitcnt vmcnt(1)
	ds_write_b128 v199, v[24:27] offset:18432
	s_waitcnt vmcnt(0)
	ds_write_b128 v199, v[28:31] offset:27648
	v_lshl_add_u64 v[80:81], s[4:5], 0, v[192:193]
	v_mfma_f32_16x16x32_bf16 v[24:27], v[180:183], v[230:233], v[68:71]
	v_lshl_add_u64 v[82:83], s[50:51], 0, v[192:193]
	s_cselect_b32 s51, s44, s31
	s_cselect_b32 s50, s43, s30
	v_add_co_u32_e64 v68, s[4:5], s14, v80
	v_mfma_f32_16x16x32_bf16 v[28:31], v[206:209], v[230:233], v[64:67]
	s_nop 0
	v_addc_co_u32_e64 v69, s[4:5], 0, v81, s[4:5]
	s_nop 0
	v_add_co_u32_e64 v64, s[4:5], s15, v80
	s_waitcnt lgkmcnt(9)
	v_mfma_f32_16x16x32_bf16 v[36:39], v[164:167], v[160:163], v[36:39]
	v_addc_co_u32_e64 v65, s[4:5], 0, v81, s[4:5]
	v_add_co_u32_e64 v66, s[4:5], s27, v80
	v_mfma_f32_16x16x32_bf16 v[32:35], v[172:175], v[160:163], v[32:35]
	s_nop 0
	v_addc_co_u32_e64 v67, s[4:5], 0, v81, s[4:5]
	v_add_co_u32_e64 v70, s[4:5], s14, v82
	v_mfma_f32_16x16x32_bf16 v[76:79], v[176:179], v[160:163], v[76:79]
	s_nop 0
	v_addc_co_u32_e64 v71, s[4:5], 0, v83, s[4:5]
	global_load_dwordx4 v[164:167], v[82:83], off
	v_mfma_f32_16x16x32_bf16 v[72:75], v[184:187], v[160:163], v[72:75]
	global_load_dwordx4 v[160:163], v[80:81], off
	v_add_co_u32_e64 v80, s[4:5], s15, v82
	v_mfma_f32_16x16x32_bf16 v[156:159], v[180:183], v[168:171], v[156:159]
	s_nop 0
	v_addc_co_u32_e64 v81, s[4:5], 0, v83, s[4:5]
	v_add_co_u32_e64 v82, s[4:5], s27, v82
	v_mfma_f32_16x16x32_bf16 v[152:155], v[206:209], v[168:171], v[152:155]
	s_nop 0
	v_addc_co_u32_e64 v83, s[4:5], 0, v83, s[4:5]
	s_cselect_b32 s5, s25, s48
	v_mfma_f32_16x16x32_bf16 v[148:151], v[210:213], v[168:171], v[148:151]
	s_cselect_b32 s4, s23, s45
	s_add_u32 s30, s30, 0x100
	s_addc_u32 s31, s31, 0
	v_mfma_f32_16x16x32_bf16 v[144:147], v[214:217], v[168:171], v[144:147]
	global_load_dwordx4 v[168:171], v[68:69], off
	global_load_dwordx4 v[172:175], v[64:65], off
	global_load_dwordx4 v[176:179], v[66:67], off
	s_add_u32 s45, s45, 0x100
	s_addc_u32 s48, s48, 0
	v_mfma_f32_16x16x32_bf16 v[140:143], v[180:183], v[188:191], v[140:143]
	v_mfma_f32_16x16x32_bf16 v[136:139], v[206:209], v[188:191], v[136:139]
	v_mfma_f32_16x16x32_bf16 v[132:135], v[210:213], v[188:191], v[132:135]
	v_mfma_f32_16x16x32_bf16 v[128:131], v[214:217], v[188:191], v[128:131]
	v_mfma_f32_16x16x32_bf16 v[124:127], v[180:183], v[218:221], v[124:127]
	v_mfma_f32_16x16x32_bf16 v[108:111], v[180:183], v[222:225], v[108:111]
	v_mfma_f32_16x16x32_bf16 v[8:11], v[180:183], v[226:229], v[92:95]
	v_mfma_f32_16x16x32_bf16 v[52:55], v[180:183], v[234:237], v[52:55]
	s_waitcnt lgkmcnt(8)
	v_mfma_f32_16x16x32_bf16 v[36:39], v[180:183], v[238:241], v[36:39]
	global_load_dwordx4 v[180:183], v[70:71], off
	global_load_dwordx4 v[184:187], v[80:81], off
	global_load_dwordx4 v[188:191], v[82:83], off
	s_waitcnt lgkmcnt(0)
	s_barrier
	s_setprio 1
	ds_read_b128 v[68:71], v196 offset:36864
	v_mfma_f32_16x16x32_bf16 v[120:123], v[206:209], v[218:221], v[120:123]
	v_mfma_f32_16x16x32_bf16 v[116:119], v[210:213], v[218:221], v[116:119]
	v_mfma_f32_16x16x32_bf16 v[104:107], v[206:209], v[222:225], v[104:107]
	v_mfma_f32_16x16x32_bf16 v[4:7], v[210:213], v[222:225], v[100:103]
	v_mfma_f32_16x16x32_bf16 v[0:3], v[214:217], v[222:225], v[96:99]
	v_mfma_f32_16x16x32_bf16 v[12:15], v[206:209], v[226:229], v[88:91]
	v_mfma_f32_16x16x32_bf16 v[16:19], v[210:213], v[226:229], v[84:87]
	v_mfma_f32_16x16x32_bf16 v[60:63], v[210:213], v[230:233], v[60:63]
	v_mfma_f32_16x16x32_bf16 v[48:51], v[206:209], v[234:237], v[48:51]
	v_mfma_f32_16x16x32_bf16 v[44:47], v[210:213], v[234:237], v[44:47]
	v_mfma_f32_16x16x32_bf16 v[32:35], v[206:209], v[238:241], v[32:35]
	ds_read_b128 v[84:87], v200
	ds_read_b128 v[206:209], v200 offset:64
	ds_read_b128 v[88:91], v196 offset:36928
	v_mfma_f32_16x16x32_bf16 v[64:67], v[210:213], v[238:241], v[76:79]
	ds_read_b128 v[96:99], v200 offset:2304
	ds_read_b128 v[210:213], v200 offset:2368
	v_mfma_f32_16x16x32_bf16 v[80:83], v[214:217], v[238:241], v[72:75]
	s_waitcnt lgkmcnt(4)
	v_mfma_f32_16x16x32_bf16 v[92:95], v[84:87], v[68:71], v[156:159]
	s_waitcnt lgkmcnt(1)
	v_mfma_f32_16x16x32_bf16 v[100:103], v[96:99], v[68:71], v[152:155]
	s_nop 2
	ds_read_b128 v[152:155], v200 offset:4608
	ds_read_b128 v[76:79], v200 offset:4672
	ds_read_b128 v[156:159], v200 offset:6912
	ds_read_b128 v[72:75], v200 offset:6976
	v_mfma_f32_16x16x32_bf16 v[112:115], v[214:217], v[218:221], v[112:115]
	v_mfma_f32_16x16x32_bf16 v[56:59], v[214:217], v[230:233], v[56:59]
	v_mfma_f32_16x16x32_bf16 v[40:43], v[214:217], v[234:237], v[40:43]
	s_waitcnt lgkmcnt(3)
	v_mfma_f32_16x16x32_bf16 v[148:151], v[152:155], v[68:71], v[148:151]
	s_waitcnt lgkmcnt(1)
	v_mfma_f32_16x16x32_bf16 v[68:71], v[156:159], v[68:71], v[144:147]
	s_nop 2
	ds_read_b128 v[144:147], v196 offset:39168
	ds_read_b128 v[214:217], v196 offset:39232
	s_waitcnt lgkmcnt(1)
	v_mfma_f32_16x16x32_bf16 v[140:143], v[84:87], v[144:147], v[140:143]
	v_mfma_f32_16x16x32_bf16 v[136:139], v[96:99], v[144:147], v[136:139]
	v_mfma_f32_16x16x32_bf16 v[132:135], v[152:155], v[144:147], v[132:135]
	v_mfma_f32_16x16x32_bf16 v[128:131], v[156:159], v[144:147], v[128:131]
	ds_read_b128 v[144:147], v196 offset:41472
	ds_read_b128 v[218:221], v196 offset:41536
	s_waitcnt lgkmcnt(1)
	v_mfma_f32_16x16x32_bf16 v[124:127], v[84:87], v[144:147], v[124:127]
	v_mfma_f32_16x16x32_bf16 v[120:123], v[96:99], v[144:147], v[120:123]
	v_mfma_f32_16x16x32_bf16 v[116:119], v[152:155], v[144:147], v[116:119]
	v_mfma_f32_16x16x32_bf16 v[112:115], v[156:159], v[144:147], v[112:115]
	ds_read_b128 v[144:147], v196 offset:43776
	ds_read_b128 v[222:225], v196 offset:43840
	s_waitcnt lgkmcnt(1)
	v_mfma_f32_16x16x32_bf16 v[108:111], v[84:87], v[144:147], v[108:111]
	v_mfma_f32_16x16x32_bf16 v[104:107], v[96:99], v[144:147], v[104:107]
	v_mfma_f32_16x16x32_bf16 v[4:7], v[152:155], v[144:147], v[4:7]
	v_mfma_f32_16x16x32_bf16 v[0:3], v[156:159], v[144:147], v[0:3]
	ds_read_b128 v[144:147], v196 offset:46080
	ds_read_b128 v[226:229], v196 offset:46144
	s_waitcnt lgkmcnt(1)
	v_mfma_f32_16x16x32_bf16 v[8:11], v[84:87], v[144:147], v[8:11]
	v_mfma_f32_16x16x32_bf16 v[12:15], v[96:99], v[144:147], v[12:15]
	v_mfma_f32_16x16x32_bf16 v[16:19], v[152:155], v[144:147], v[16:19]
	v_mfma_f32_16x16x32_bf16 v[20:23], v[156:159], v[144:147], v[20:23]
	ds_read_b128 v[144:147], v196 offset:48384
	ds_read_b128 v[230:233], v196 offset:48448
	s_waitcnt lgkmcnt(1)
	v_mfma_f32_16x16x32_bf16 v[24:27], v[84:87], v[144:147], v[24:27]
	v_mfma_f32_16x16x32_bf16 v[28:31], v[96:99], v[144:147], v[28:31]
	v_mfma_f32_16x16x32_bf16 v[60:63], v[152:155], v[144:147], v[60:63]
	v_mfma_f32_16x16x32_bf16 v[56:59], v[156:159], v[144:147], v[56:59]
	ds_read_b128 v[144:147], v196 offset:50688
	ds_read_b128 v[234:237], v196 offset:50752
	s_waitcnt lgkmcnt(1)
	v_mfma_f32_16x16x32_bf16 v[52:55], v[84:87], v[144:147], v[52:55]
	v_mfma_f32_16x16x32_bf16 v[48:51], v[96:99], v[144:147], v[48:51]
	v_mfma_f32_16x16x32_bf16 v[44:47], v[152:155], v[144:147], v[44:47]
	v_mfma_f32_16x16x32_bf16 v[40:43], v[156:159], v[144:147], v[40:43]
	ds_read_b128 v[144:147], v196 offset:52992
	ds_read_b128 v[238:241], v196 offset:53056
	s_waitcnt lgkmcnt(1)
	v_mfma_f32_16x16x32_bf16 v[242:245], v[152:155], v[144:147], v[64:67]
	v_mfma_f32_16x16x32_bf16 v[152:155], v[210:213], v[88:91], v[100:103]
	v_mfma_f32_16x16x32_bf16 v[100:103], v[76:79], v[222:225], v[4:7]
	s_nop 2
	v_lshl_add_u64 v[4:5], s[4:5], 0, v[192:193]
	v_mfma_f32_16x16x32_bf16 v[246:249], v[156:159], v[144:147], v[80:83]
	v_lshl_add_u64 v[6:7], s[50:51], 0, v[192:193]
	v_mfma_f32_16x16x32_bf16 v[156:159], v[206:209], v[88:91], v[92:95]
	v_mfma_f32_16x16x32_bf16 v[92:95], v[206:209], v[226:229], v[8:11]
	s_nop 2
	v_add_co_u32_e64 v8, s[4:5], s14, v4
	v_mfma_f32_16x16x32_bf16 v[36:39], v[84:87], v[144:147], v[36:39]
	s_nop 0
	v_addc_co_u32_e64 v9, s[4:5], 0, v5, s[4:5]
	v_mfma_f32_16x16x32_bf16 v[32:35], v[96:99], v[144:147], v[32:35]
	v_mfma_f32_16x16x32_bf16 v[148:151], v[76:79], v[88:91], v[148:151]
	v_mfma_f32_16x16x32_bf16 v[144:147], v[72:75], v[88:91], v[68:71]
	v_mfma_f32_16x16x32_bf16 v[88:91], v[210:213], v[226:229], v[12:15]
	s_nop 2
	v_add_co_u32_e64 v12, s[4:5], s15, v4
	v_mfma_f32_16x16x32_bf16 v[84:87], v[76:79], v[226:229], v[16:19]
	s_nop 0
	v_addc_co_u32_e64 v13, s[4:5], 0, v5, s[4:5]
	s_nop 0
	v_add_co_u32_e64 v16, s[4:5], s27, v4
	v_mfma_f32_16x16x32_bf16 v[80:83], v[72:75], v[226:229], v[20:23]
	s_nop 0
	v_addc_co_u32_e64 v17, s[4:5], 0, v5, s[4:5]
	s_nop 0
	v_add_co_u32_e64 v20, s[4:5], s14, v6
	v_mfma_f32_16x16x32_bf16 v[68:71], v[206:209], v[230:233], v[24:27]
	s_nop 0
	v_addc_co_u32_e64 v21, s[4:5], 0, v7, s[4:5]
	s_nop 0
	v_add_co_u32_e64 v24, s[4:5], s15, v6
	v_mfma_f32_16x16x32_bf16 v[64:67], v[210:213], v[230:233], v[28:31]
	s_nop 0
	v_addc_co_u32_e64 v25, s[4:5], 0, v7, s[4:5]
	s_nop 0
	v_add_co_u32_e64 v28, s[4:5], s27, v6
	v_mfma_f32_16x16x32_bf16 v[96:99], v[72:75], v[222:225], v[0:3]
	s_nop 0
	v_addc_co_u32_e64 v29, s[4:5], 0, v7, s[4:5]
	s_nop 0
	global_load_dwordx4 v[0:3], v[6:7], off
	s_nop 0
	global_load_dwordx4 v[4:7], v[4:5], off
	s_nop 0
	global_load_dwordx4 v[8:11], v[8:9], off
	s_nop 0
	global_load_dwordx4 v[12:15], v[12:13], off
	s_nop 0
	global_load_dwordx4 v[16:19], v[16:17], off
	s_nop 0
	global_load_dwordx4 v[20:23], v[20:21], off
	s_nop 0
	global_load_dwordx4 v[24:27], v[24:25], off
	v_mfma_f32_16x16x32_bf16 v[140:143], v[206:209], v[214:217], v[140:143]
	global_load_dwordx4 v[28:31], v[28:29], off
	s_setprio 0
	s_waitcnt vmcnt(14)
	ds_write_b128 v194, v[160:163]
	ds_write_b128 v195, v[164:167]
	s_waitcnt vmcnt(13)
	ds_write_b128 v194, v[168:171] offset:9216
	s_waitcnt vmcnt(12)
	ds_write_b128 v194, v[172:175] offset:18432
	s_waitcnt vmcnt(11)
	ds_write_b128 v194, v[176:179] offset:27648
	s_waitcnt vmcnt(10)
	ds_write_b128 v195, v[180:183] offset:9216
	s_waitcnt vmcnt(9)
	ds_write_b128 v195, v[184:187] offset:18432
	s_waitcnt vmcnt(8)
	ds_write_b128 v195, v[188:191] offset:27648
	s_waitcnt lgkmcnt(0)
	v_mfma_f32_16x16x32_bf16 v[136:139], v[210:213], v[214:217], v[136:139]
	s_barrier
	s_setprio 1
	v_mfma_f32_16x16x32_bf16 v[132:135], v[76:79], v[214:217], v[132:135]
	v_mfma_f32_16x16x32_bf16 v[128:131], v[72:75], v[214:217], v[128:131]
	v_mfma_f32_16x16x32_bf16 v[124:127], v[206:209], v[218:221], v[124:127]
	v_mfma_f32_16x16x32_bf16 v[120:123], v[210:213], v[218:221], v[120:123]
	v_mfma_f32_16x16x32_bf16 v[116:119], v[76:79], v[218:221], v[116:119]
	v_mfma_f32_16x16x32_bf16 v[112:115], v[72:75], v[218:221], v[112:115]
	v_mfma_f32_16x16x32_bf16 v[108:111], v[206:209], v[222:225], v[108:111]
	v_mfma_f32_16x16x32_bf16 v[104:107], v[210:213], v[222:225], v[104:107]
	v_mfma_f32_16x16x32_bf16 v[60:63], v[76:79], v[230:233], v[60:63]
	v_mfma_f32_16x16x32_bf16 v[56:59], v[72:75], v[230:233], v[56:59]
	v_mfma_f32_16x16x32_bf16 v[52:55], v[206:209], v[234:237], v[52:55]
	v_mfma_f32_16x16x32_bf16 v[48:51], v[210:213], v[234:237], v[48:51]
	v_mfma_f32_16x16x32_bf16 v[44:47], v[76:79], v[234:237], v[44:47]
	v_mfma_f32_16x16x32_bf16 v[40:43], v[72:75], v[234:237], v[40:43]
	v_mfma_f32_16x16x32_bf16 v[36:39], v[206:209], v[238:241], v[36:39]
	v_mfma_f32_16x16x32_bf16 v[32:35], v[210:213], v[238:241], v[32:35]
	v_mfma_f32_16x16x32_bf16 v[76:79], v[76:79], v[238:241], v[242:245]
	v_mfma_f32_16x16x32_bf16 v[72:75], v[72:75], v[238:241], v[246:249]
	s_cbranch_vccz .LBB0_195
	s_mul_i32 s98, s26, 0x1040
	s_lshl_b32 s99, s28, 1
	s_add_u32 s98, s98, s99
	s_add_u32 s100, s16, s98
	s_addc_u32 s101, s17, 0
	v_and_b32_e32 v160, 15, v197
	v_and_b32_e32 v161, 0x80, v201
	v_add_u32_e32 v160, v160, v161
	v_mul_u32_u24_e32 v160, 0x1040, v160
	v_and_b32_e32 v161, 0xc0, v197
	v_lshl_add_u32 v160, v161, 1, v160
	v_and_b32_e32 v161, 4, v201
	v_lshl_add_u32 v160, v161, 3, v160
	v_and_b32_e32 v161, 8, v201
	v_lshl_add_u32 v160, v161, 1, v160
	v_cvt_pk_bf16_f32 v156, v156, v157
	v_cvt_pk_bf16_f32 v157, v158, v159
	v_cvt_pk_bf16_f32 v158, v152, v153
	v_cvt_pk_bf16_f32 v159, v154, v155
	v_cvt_pk_bf16_f32 v148, v148, v149
	v_cvt_pk_bf16_f32 v149, v150, v151
	v_cvt_pk_bf16_f32 v150, v144, v145
	v_cvt_pk_bf16_f32 v151, v146, v147
	v_permlane16_swap_b32_e32 v156, v158
	v_permlane16_swap_b32_e32 v157, v159
	v_permlane16_swap_b32_e32 v148, v150
	v_permlane16_swap_b32_e32 v149, v151
	global_store_dwordx4 v160, v[156:159], s[100:101] sc1
	global_store_dwordx4 v160, v[148:151], s[100:101] offset:64 sc1
	s_add_u32 s100, s100, 0x10400
	s_addc_u32 s101, s101, 0
	v_cvt_pk_bf16_f32 v140, v140, v141
	v_cvt_pk_bf16_f32 v141, v142, v143
	v_cvt_pk_bf16_f32 v142, v136, v137
	v_cvt_pk_bf16_f32 v143, v138, v139
	v_cvt_pk_bf16_f32 v132, v132, v133
	v_cvt_pk_bf16_f32 v133, v134, v135
	v_cvt_pk_bf16_f32 v134, v128, v129
	v_cvt_pk_bf16_f32 v135, v130, v131
	v_permlane16_swap_b32_e32 v140, v142
	v_permlane16_swap_b32_e32 v141, v143
	v_permlane16_swap_b32_e32 v132, v134
	v_permlane16_swap_b32_e32 v133, v135
	global_store_dwordx4 v160, v[140:143], s[100:101] sc1
	global_store_dwordx4 v160, v[132:135], s[100:101] offset:64 sc1
	s_add_u32 s100, s100, 0x10400
	s_addc_u32 s101, s101, 0
	v_cvt_pk_bf16_f32 v124, v124, v125
	v_cvt_pk_bf16_f32 v125, v126, v127
	v_cvt_pk_bf16_f32 v126, v120, v121
	v_cvt_pk_bf16_f32 v127, v122, v123
	v_cvt_pk_bf16_f32 v116, v116, v117
	v_cvt_pk_bf16_f32 v117, v118, v119
	v_cvt_pk_bf16_f32 v118, v112, v113
	v_cvt_pk_bf16_f32 v119, v114, v115
	v_permlane16_swap_b32_e32 v124, v126
	v_permlane16_swap_b32_e32 v125, v127
	v_permlane16_swap_b32_e32 v116, v118
	v_permlane16_swap_b32_e32 v117, v119
	global_store_dwordx4 v160, v[124:127], s[100:101] sc1
	global_store_dwordx4 v160, v[116:119], s[100:101] offset:64 sc1
	s_add_u32 s100, s100, 0x10400
	s_addc_u32 s101, s101, 0
	v_cvt_pk_bf16_f32 v108, v108, v109
	v_cvt_pk_bf16_f32 v109, v110, v111
	v_cvt_pk_bf16_f32 v110, v104, v105
	v_cvt_pk_bf16_f32 v111, v106, v107
	v_cvt_pk_bf16_f32 v100, v100, v101
	v_cvt_pk_bf16_f32 v101, v102, v103
	v_cvt_pk_bf16_f32 v102, v96, v97
	v_cvt_pk_bf16_f32 v103, v98, v99
	v_permlane16_swap_b32_e32 v108, v110
	v_permlane16_swap_b32_e32 v109, v111
	v_permlane16_swap_b32_e32 v100, v102
	v_permlane16_swap_b32_e32 v101, v103
	global_store_dwordx4 v160, v[108:111], s[100:101] sc1
	global_store_dwordx4 v160, v[100:103], s[100:101] offset:64 sc1
	s_add_u32 s100, s100, 0x10400
	s_addc_u32 s101, s101, 0
	v_cvt_pk_bf16_f32 v92, v92, v93
	v_cvt_pk_bf16_f32 v93, v94, v95
	v_cvt_pk_bf16_f32 v94, v88, v89
	v_cvt_pk_bf16_f32 v95, v90, v91
	v_cvt_pk_bf16_f32 v84, v84, v85
	v_cvt_pk_bf16_f32 v85, v86, v87
	v_cvt_pk_bf16_f32 v86, v80, v81
	v_cvt_pk_bf16_f32 v87, v82, v83
	v_permlane16_swap_b32_e32 v92, v94
	v_permlane16_swap_b32_e32 v93, v95
	v_permlane16_swap_b32_e32 v84, v86
	v_permlane16_swap_b32_e32 v85, v87
	global_store_dwordx4 v160, v[92:95], s[100:101] sc1
	global_store_dwordx4 v160, v[84:87], s[100:101] offset:64 sc1
	s_add_u32 s100, s100, 0x10400
	s_addc_u32 s101, s101, 0
	v_cvt_pk_bf16_f32 v68, v68, v69
	v_cvt_pk_bf16_f32 v69, v70, v71
	v_cvt_pk_bf16_f32 v70, v64, v65
	v_cvt_pk_bf16_f32 v71, v66, v67
	v_cvt_pk_bf16_f32 v60, v60, v61
	v_cvt_pk_bf16_f32 v61, v62, v63
	v_cvt_pk_bf16_f32 v62, v56, v57
	v_cvt_pk_bf16_f32 v63, v58, v59
	v_permlane16_swap_b32_e32 v68, v70
	v_permlane16_swap_b32_e32 v69, v71
	v_permlane16_swap_b32_e32 v60, v62
	v_permlane16_swap_b32_e32 v61, v63
	global_store_dwordx4 v160, v[68:71], s[100:101] sc1
	global_store_dwordx4 v160, v[60:63], s[100:101] offset:64 sc1
	s_add_u32 s100, s100, 0x10400
	s_addc_u32 s101, s101, 0
	v_cvt_pk_bf16_f32 v52, v52, v53
	v_cvt_pk_bf16_f32 v53, v54, v55
	v_cvt_pk_bf16_f32 v54, v48, v49
	v_cvt_pk_bf16_f32 v55, v50, v51
	v_cvt_pk_bf16_f32 v44, v44, v45
	v_cvt_pk_bf16_f32 v45, v46, v47
	v_cvt_pk_bf16_f32 v46, v40, v41
	v_cvt_pk_bf16_f32 v47, v42, v43
	v_permlane16_swap_b32_e32 v52, v54
	v_permlane16_swap_b32_e32 v53, v55
	v_permlane16_swap_b32_e32 v44, v46
	v_permlane16_swap_b32_e32 v45, v47
	global_store_dwordx4 v160, v[52:55], s[100:101] sc1
	global_store_dwordx4 v160, v[44:47], s[100:101] offset:64 sc1
	s_add_u32 s100, s100, 0x10400
	s_addc_u32 s101, s101, 0
	v_cvt_pk_bf16_f32 v36, v36, v37
	v_cvt_pk_bf16_f32 v37, v38, v39
	v_cvt_pk_bf16_f32 v38, v32, v33
	v_cvt_pk_bf16_f32 v39, v34, v35
	v_cvt_pk_bf16_f32 v76, v76, v77
	v_cvt_pk_bf16_f32 v77, v78, v79
	v_cvt_pk_bf16_f32 v78, v72, v73
	v_cvt_pk_bf16_f32 v79, v74, v75
	v_permlane16_swap_b32_e32 v36, v38
	v_permlane16_swap_b32_e32 v37, v39
	v_permlane16_swap_b32_e32 v76, v78
	v_permlane16_swap_b32_e32 v77, v79
	global_store_dwordx4 v160, v[36:39], s[100:101] sc1
	global_store_dwordx4 v160, v[76:79], s[100:101] offset:64 sc1
	s_and_b64 vcc, exec, s[20:21]
	s_mov_b32 s28, s24
	s_mov_b32 s26, s22
	s_mov_b64 s[30:31], s[12:13]
	s_mov_b64 s[4:5], s[10:11]
	s_cbranch_vccz .LBB0_192

.LBB0_1020:
	ds_read_b128 v[160:163], v202
	ds_read_b128 v[164:167], v203
	ds_read_b128 v[180:183], v203 offset:64
	ds_read_b128 v[168:171], v202 offset:64
	ds_read_b128 v[172:175], v203 offset:2304
	ds_read_b128 v[192:195], v203 offset:2368
	ds_read_b128 v[176:179], v203 offset:4608
	ds_read_b128 v[210:213], v203 offset:4672
	ds_read_b128 v[184:187], v203 offset:6912
	ds_read_b128 v[214:217], v203 offset:6976
	s_waitcnt lgkmcnt(8)
	v_mfma_f32_16x16x32_bf16 v[156:159], v[164:167], v[160:163], v[156:159]
	s_add_i32 s81, s80, 2
	s_add_u32 s82, s58, 0xffffff80
	s_addc_u32 s83, s59, -1
	s_waitcnt lgkmcnt(5)
	v_mfma_f32_16x16x32_bf16 v[152:155], v[172:175], v[160:163], v[152:155]
	s_add_u32 s84, s60, 0xffffff80
	s_addc_u32 s85, s61, -1
	s_cmp_lt_u32 s80, 6
	s_waitcnt lgkmcnt(3)
	v_mfma_f32_16x16x32_bf16 v[148:151], v[176:179], v[160:163], v[148:151]
	s_cselect_b32 s82, s82, s42
	s_cselect_b32 s83, s83, s43
	s_cselect_b32 s84, s84, s44
	s_waitcnt lgkmcnt(1)
	v_mfma_f32_16x16x32_bf16 v[144:147], v[184:187], v[160:163], v[144:147]
	ds_read_b128 v[160:163], v202 offset:2304
	ds_read_b128 v[188:191], v202 offset:2368
	s_cselect_b32 s85, s85, s45
	s_cmp_lt_u32 s80, 5
	s_waitcnt lgkmcnt(1)
	v_mfma_f32_16x16x32_bf16 v[140:143], v[164:167], v[160:163], v[140:143]
	v_mfma_f32_16x16x32_bf16 v[136:139], v[172:175], v[160:163], v[136:139]
	v_mfma_f32_16x16x32_bf16 v[132:135], v[176:179], v[160:163], v[132:135]
	v_mfma_f32_16x16x32_bf16 v[128:131], v[184:187], v[160:163], v[128:131]
	ds_read_b128 v[160:163], v202 offset:4608
	ds_read_b128 v[218:221], v202 offset:4672
	s_waitcnt lgkmcnt(1)
	v_mfma_f32_16x16x32_bf16 v[124:127], v[164:167], v[160:163], v[124:127]
	v_mfma_f32_16x16x32_bf16 v[120:123], v[172:175], v[160:163], v[120:123]
	v_mfma_f32_16x16x32_bf16 v[116:119], v[176:179], v[160:163], v[116:119]
	v_mfma_f32_16x16x32_bf16 v[112:115], v[184:187], v[160:163], v[112:115]
	ds_read_b128 v[160:163], v202 offset:6912
	ds_read_b128 v[222:225], v202 offset:6976
	s_waitcnt lgkmcnt(1)
	v_mfma_f32_16x16x32_bf16 v[108:111], v[164:167], v[160:163], v[108:111]
	v_mfma_f32_16x16x32_bf16 v[104:107], v[172:175], v[160:163], v[104:107]
	v_mfma_f32_16x16x32_bf16 v[100:103], v[176:179], v[160:163], v[100:103]
	v_mfma_f32_16x16x32_bf16 v[96:99], v[184:187], v[160:163], v[96:99]
	ds_read_b128 v[160:163], v202 offset:9216
	ds_read_b128 v[226:229], v202 offset:9280
	s_waitcnt lgkmcnt(1)
	v_mfma_f32_16x16x32_bf16 v[92:95], v[164:167], v[160:163], v[92:95]
	v_mfma_f32_16x16x32_bf16 v[88:91], v[172:175], v[160:163], v[88:91]
	v_mfma_f32_16x16x32_bf16 v[80:83], v[176:179], v[160:163], v[80:83]
	v_mfma_f32_16x16x32_bf16 v[84:87], v[184:187], v[160:163], v[84:87]
	ds_read_b128 v[160:163], v202 offset:11520
	ds_read_b128 v[230:233], v202 offset:11584
	s_waitcnt lgkmcnt(1)
	v_mfma_f32_16x16x32_bf16 v[76:79], v[164:167], v[160:163], v[76:79]
	v_mfma_f32_16x16x32_bf16 v[72:75], v[172:175], v[160:163], v[72:75]
	v_mfma_f32_16x16x32_bf16 v[68:71], v[176:179], v[160:163], v[68:71]
	v_mfma_f32_16x16x32_bf16 v[64:67], v[184:187], v[160:163], v[64:67]
	ds_read_b128 v[160:163], v202 offset:13824
	ds_read_b128 v[234:237], v202 offset:13888
	s_waitcnt lgkmcnt(1)
	v_mfma_f32_16x16x32_bf16 v[60:63], v[164:167], v[160:163], v[60:63]
	v_mfma_f32_16x16x32_bf16 v[56:59], v[172:175], v[160:163], v[56:59]
	v_mfma_f32_16x16x32_bf16 v[52:55], v[176:179], v[160:163], v[52:55]
	v_mfma_f32_16x16x32_bf16 v[48:51], v[184:187], v[160:163], v[48:51]
	ds_read_b128 v[160:163], v202 offset:16128
	ds_read_b128 v[238:241], v202 offset:16192
	s_setprio 0
	s_waitcnt vmcnt(6)
	ds_write_b128 v200, v[4:7] offset:36864
	s_waitcnt vmcnt(5)
	ds_write_b128 v200, v[8:11] offset:46080
	s_waitcnt vmcnt(4)
	ds_write_b128 v200, v[12:15] offset:55296
	s_waitcnt vmcnt(3)
	ds_write_b128 v200, v[16:19] offset:64512
	v_mfma_f32_16x16x32_bf16 v[16:19], v[210:213], v[226:229], v[80:83]
	s_waitcnt vmcnt(3)
	ds_write_b128 v208, v[0:3]
	s_waitcnt vmcnt(2)
	ds_write_b128 v208, v[20:23] offset:9216
	s_waitcnt vmcnt(1)
	ds_write_b128 v208, v[24:27] offset:18432
	v_lshl_add_u64 v[80:81], s[82:83], 0, v[196:197]
	s_waitcnt vmcnt(0)
	ds_write_b128 v208, v[28:31] offset:27648
	v_mfma_f32_16x16x32_bf16 v[24:27], v[180:183], v[230:233], v[76:79]
	v_lshl_add_u64 v[82:83], s[84:85], 0, v[196:197]
	s_cselect_b32 s82, s58, s49
	s_cselect_b32 s83, s59, s77
	v_add_co_u32_e32 v76, vcc, s57, v80
	v_mfma_f32_16x16x32_bf16 v[28:31], v[192:195], v[230:233], v[72:75]
	s_nop 0
	v_addc_co_u32_e32 v77, vcc, 0, v81, vcc
	s_cselect_b32 s84, s60, s78
	v_add_co_u32_e32 v72, vcc, s63, v80
	s_waitcnt lgkmcnt(9)
	v_mfma_f32_16x16x32_bf16 v[40:43], v[164:167], v[160:163], v[40:43]
	v_addc_co_u32_e32 v73, vcc, 0, v81, vcc
	v_add_co_u32_e32 v74, vcc, s64, v80
	v_mfma_f32_16x16x32_bf16 v[36:39], v[172:175], v[160:163], v[36:39]
	s_nop 0
	v_addc_co_u32_e32 v75, vcc, 0, v81, vcc
	v_add_co_u32_e32 v78, vcc, s57, v82
	v_mfma_f32_16x16x32_bf16 v[32:35], v[176:179], v[160:163], v[32:35]
	s_nop 0
	v_addc_co_u32_e32 v79, vcc, 0, v83, vcc
	global_load_dwordx4 v[164:167], v[82:83], off
	v_mfma_f32_16x16x32_bf16 v[44:47], v[184:187], v[160:163], v[44:47]
	global_load_dwordx4 v[160:163], v[80:81], off
	v_add_co_u32_e32 v80, vcc, s63, v82
	v_mfma_f32_16x16x32_bf16 v[156:159], v[180:183], v[168:171], v[156:159]
	s_nop 0
	v_addc_co_u32_e32 v81, vcc, 0, v83, vcc
	v_add_co_u32_e32 v82, vcc, s64, v82
	v_mfma_f32_16x16x32_bf16 v[152:155], v[192:195], v[168:171], v[152:155]
	s_nop 0
	v_addc_co_u32_e32 v83, vcc, 0, v83, vcc
	s_cselect_b32 s85, s61, s79
	v_mfma_f32_16x16x32_bf16 v[148:151], v[210:213], v[168:171], v[148:151]
	s_add_u32 s60, s60, 0x100
	s_addc_u32 s61, s61, 0
	s_add_u32 s58, s58, 0x100
	v_mfma_f32_16x16x32_bf16 v[144:147], v[214:217], v[168:171], v[144:147]
	global_load_dwordx4 v[168:171], v[76:77], off
	global_load_dwordx4 v[172:175], v[72:73], off
	global_load_dwordx4 v[176:179], v[74:75], off
	s_addc_u32 s59, s59, 0
	s_cmp_gt_u32 s80, 5
	v_mfma_f32_16x16x32_bf16 v[140:143], v[180:183], v[188:191], v[140:143]
	s_mov_b32 s80, s81
	v_mfma_f32_16x16x32_bf16 v[136:139], v[192:195], v[188:191], v[136:139]
	v_mfma_f32_16x16x32_bf16 v[132:135], v[210:213], v[188:191], v[132:135]
	v_mfma_f32_16x16x32_bf16 v[128:131], v[214:217], v[188:191], v[128:131]
	v_mfma_f32_16x16x32_bf16 v[124:127], v[180:183], v[218:221], v[124:127]
	v_mfma_f32_16x16x32_bf16 v[108:111], v[180:183], v[222:225], v[108:111]
	v_mfma_f32_16x16x32_bf16 v[0:3], v[180:183], v[226:229], v[92:95]
	v_mfma_f32_16x16x32_bf16 v[60:63], v[180:183], v[234:237], v[60:63]
	s_waitcnt lgkmcnt(8)
	v_mfma_f32_16x16x32_bf16 v[40:43], v[180:183], v[238:241], v[40:43]
	global_load_dwordx4 v[180:183], v[78:79], off
	global_load_dwordx4 v[184:187], v[80:81], off
	global_load_dwordx4 v[188:191], v[82:83], off
	s_waitcnt lgkmcnt(0)
	s_barrier
	s_setprio 1
	ds_read_b128 v[72:75], v202 offset:36864
	v_mfma_f32_16x16x32_bf16 v[116:119], v[210:213], v[218:221], v[116:119]
	v_mfma_f32_16x16x32_bf16 v[112:115], v[214:217], v[218:221], v[112:115]
	v_mfma_f32_16x16x32_bf16 v[4:7], v[210:213], v[222:225], v[100:103]
	v_mfma_f32_16x16x32_bf16 v[8:11], v[214:217], v[222:225], v[96:99]
	v_mfma_f32_16x16x32_bf16 v[20:23], v[214:217], v[226:229], v[84:87]
	v_mfma_f32_16x16x32_bf16 v[68:71], v[210:213], v[230:233], v[68:71]
	v_mfma_f32_16x16x32_bf16 v[64:67], v[214:217], v[230:233], v[64:67]
	v_mfma_f32_16x16x32_bf16 v[52:55], v[210:213], v[234:237], v[52:55]
	v_mfma_f32_16x16x32_bf16 v[48:51], v[214:217], v[234:237], v[48:51]
	v_mfma_f32_16x16x32_bf16 v[32:35], v[210:213], v[238:241], v[32:35]
	ds_read_b128 v[80:83], v209
	ds_read_b128 v[210:213], v209 offset:64
	ds_read_b128 v[84:87], v202 offset:36928
	v_mfma_f32_16x16x32_bf16 v[76:79], v[214:217], v[238:241], v[44:47]
	ds_read_b128 v[92:95], v209 offset:2304
	ds_read_b128 v[214:217], v209 offset:2368
	v_mfma_f32_16x16x32_bf16 v[120:123], v[192:195], v[218:221], v[120:123]
	ds_read_b128 v[100:103], v209 offset:4608
	ds_read_b128 v[218:221], v209 offset:4672
	s_waitcnt lgkmcnt(3)
	v_mfma_f32_16x16x32_bf16 v[96:99], v[92:95], v[72:75], v[152:155]
	s_nop 2
	ds_read_b128 v[152:155], v209 offset:6912
	ds_read_b128 v[44:47], v209 offset:6976
	v_mfma_f32_16x16x32_bf16 v[104:107], v[192:195], v[222:225], v[104:107]
	v_mfma_f32_16x16x32_bf16 v[12:15], v[192:195], v[226:229], v[88:91]
	v_mfma_f32_16x16x32_bf16 v[88:91], v[80:83], v[72:75], v[156:159]
	s_waitcnt lgkmcnt(3)
	v_mfma_f32_16x16x32_bf16 v[148:151], v[100:103], v[72:75], v[148:151]
	s_waitcnt lgkmcnt(1)
	v_mfma_f32_16x16x32_bf16 v[72:75], v[152:155], v[72:75], v[144:147]
	s_nop 2
	ds_read_b128 v[144:147], v202 offset:39168
	ds_read_b128 v[222:225], v202 offset:39232
	s_waitcnt lgkmcnt(1)
	v_mfma_f32_16x16x32_bf16 v[140:143], v[80:83], v[144:147], v[140:143]
	v_mfma_f32_16x16x32_bf16 v[136:139], v[92:95], v[144:147], v[136:139]
	v_mfma_f32_16x16x32_bf16 v[132:135], v[100:103], v[144:147], v[132:135]
	v_mfma_f32_16x16x32_bf16 v[128:131], v[152:155], v[144:147], v[128:131]
	ds_read_b128 v[144:147], v202 offset:41472
	ds_read_b128 v[226:229], v202 offset:41536
	s_waitcnt lgkmcnt(1)
	v_mfma_f32_16x16x32_bf16 v[124:127], v[80:83], v[144:147], v[124:127]
	v_mfma_f32_16x16x32_bf16 v[120:123], v[92:95], v[144:147], v[120:123]
	v_mfma_f32_16x16x32_bf16 v[116:119], v[100:103], v[144:147], v[116:119]
	v_mfma_f32_16x16x32_bf16 v[112:115], v[152:155], v[144:147], v[112:115]
	ds_read_b128 v[144:147], v202 offset:43776
	ds_read_b128 v[230:233], v202 offset:43840
	v_mfma_f32_16x16x32_bf16 v[56:59], v[192:195], v[234:237], v[56:59]
	s_waitcnt lgkmcnt(1)
	v_mfma_f32_16x16x32_bf16 v[108:111], v[80:83], v[144:147], v[108:111]
	v_mfma_f32_16x16x32_bf16 v[104:107], v[92:95], v[144:147], v[104:107]
	v_mfma_f32_16x16x32_bf16 v[4:7], v[100:103], v[144:147], v[4:7]
	v_mfma_f32_16x16x32_bf16 v[8:11], v[152:155], v[144:147], v[8:11]
	ds_read_b128 v[144:147], v202 offset:46080
	ds_read_b128 v[234:237], v202 offset:46144
	v_mfma_f32_16x16x32_bf16 v[36:39], v[192:195], v[238:241], v[36:39]
	s_waitcnt lgkmcnt(1)
	v_mfma_f32_16x16x32_bf16 v[0:3], v[80:83], v[144:147], v[0:3]
	v_mfma_f32_16x16x32_bf16 v[12:15], v[92:95], v[144:147], v[12:15]
	v_mfma_f32_16x16x32_bf16 v[16:19], v[100:103], v[144:147], v[16:19]
	v_mfma_f32_16x16x32_bf16 v[20:23], v[152:155], v[144:147], v[20:23]
	ds_read_b128 v[144:147], v202 offset:48384
	ds_read_b128 v[238:241], v202 offset:48448
	s_waitcnt lgkmcnt(1)
	v_mfma_f32_16x16x32_bf16 v[24:27], v[80:83], v[144:147], v[24:27]
	v_mfma_f32_16x16x32_bf16 v[28:31], v[92:95], v[144:147], v[28:31]
	v_mfma_f32_16x16x32_bf16 v[68:71], v[100:103], v[144:147], v[68:71]
	v_mfma_f32_16x16x32_bf16 v[64:67], v[152:155], v[144:147], v[64:67]
	ds_read_b128 v[144:147], v202 offset:50688
	ds_read_b128 v[242:245], v202 offset:50752
	s_waitcnt lgkmcnt(1)
	v_mfma_f32_16x16x32_bf16 v[60:63], v[80:83], v[144:147], v[60:63]
	v_mfma_f32_16x16x32_bf16 v[56:59], v[92:95], v[144:147], v[56:59]
	v_mfma_f32_16x16x32_bf16 v[52:55], v[100:103], v[144:147], v[52:55]
	v_mfma_f32_16x16x32_bf16 v[48:51], v[152:155], v[144:147], v[48:51]
	ds_read_b128 v[144:147], v202 offset:52992
	ds_read_b128 v[192:195], v202 offset:53056
	s_waitcnt lgkmcnt(1)
	v_mfma_f32_16x16x32_bf16 v[32:35], v[100:103], v[144:147], v[32:35]
	v_mfma_f32_16x16x32_bf16 v[100:103], v[218:221], v[230:233], v[4:7]
	s_nop 2
	v_lshl_add_u64 v[4:5], s[82:83], 0, v[196:197]
	v_mfma_f32_16x16x32_bf16 v[246:249], v[152:155], v[144:147], v[76:79]
	v_lshl_add_u64 v[6:7], s[84:85], 0, v[196:197]
	v_mfma_f32_16x16x32_bf16 v[152:155], v[214:217], v[84:87], v[96:99]
	v_mfma_f32_16x16x32_bf16 v[96:99], v[44:47], v[230:233], v[8:11]
	s_nop 2
	v_add_co_u32_e32 v8, vcc, s57, v4
	v_mfma_f32_16x16x32_bf16 v[156:159], v[210:213], v[84:87], v[88:91]
	s_nop 0
	v_addc_co_u32_e32 v9, vcc, 0, v5, vcc
	v_mfma_f32_16x16x32_bf16 v[88:91], v[214:217], v[234:237], v[12:15]
	s_nop 2
	v_add_co_u32_e32 v12, vcc, s63, v4
	v_mfma_f32_16x16x32_bf16 v[40:43], v[80:83], v[144:147], v[40:43]
	s_nop 0
	v_addc_co_u32_e32 v13, vcc, 0, v5, vcc
	v_mfma_f32_16x16x32_bf16 v[80:83], v[218:221], v[234:237], v[16:19]
	s_nop 2
	v_add_co_u32_e32 v16, vcc, s64, v4
	v_mfma_f32_16x16x32_bf16 v[36:39], v[92:95], v[144:147], v[36:39]
	s_nop 0
	v_addc_co_u32_e32 v17, vcc, 0, v5, vcc
	v_mfma_f32_16x16x32_bf16 v[148:151], v[218:221], v[84:87], v[148:151]
	v_mfma_f32_16x16x32_bf16 v[144:147], v[44:47], v[84:87], v[72:75]
	v_mfma_f32_16x16x32_bf16 v[84:87], v[44:47], v[234:237], v[20:23]
	s_nop 2
	v_add_co_u32_e32 v20, vcc, s57, v6
	v_mfma_f32_16x16x32_bf16 v[76:79], v[210:213], v[238:241], v[24:27]
	s_nop 0
	v_addc_co_u32_e32 v21, vcc, 0, v7, vcc
	s_nop 0
	v_add_co_u32_e32 v24, vcc, s63, v6
	v_mfma_f32_16x16x32_bf16 v[72:75], v[214:217], v[238:241], v[28:31]
	s_nop 0
	v_addc_co_u32_e32 v25, vcc, 0, v7, vcc
	s_nop 0
	v_add_co_u32_e32 v28, vcc, s64, v6
	v_mfma_f32_16x16x32_bf16 v[92:95], v[210:213], v[234:237], v[0:3]
	s_nop 0
	v_addc_co_u32_e32 v29, vcc, 0, v7, vcc
	s_nop 0
	global_load_dwordx4 v[0:3], v[6:7], off
	s_nop 0
	global_load_dwordx4 v[4:7], v[4:5], off
	s_nop 0
	global_load_dwordx4 v[8:11], v[8:9], off
	s_nop 0
	global_load_dwordx4 v[12:15], v[12:13], off
	s_nop 0
	global_load_dwordx4 v[16:19], v[16:17], off
	s_nop 0
	global_load_dwordx4 v[20:23], v[20:21], off
	s_nop 0
	global_load_dwordx4 v[24:27], v[24:25], off
	v_mfma_f32_16x16x32_bf16 v[140:143], v[210:213], v[222:225], v[140:143]
	global_load_dwordx4 v[28:31], v[28:29], off
	s_setprio 0
	s_waitcnt vmcnt(14)
	ds_write_b128 v200, v[160:163]
	ds_write_b128 v207, v[164:167]
	s_waitcnt vmcnt(13)
	ds_write_b128 v200, v[168:171] offset:9216
	s_waitcnt vmcnt(12)
	ds_write_b128 v200, v[172:175] offset:18432
	s_waitcnt vmcnt(11)
	ds_write_b128 v200, v[176:179] offset:27648
	s_waitcnt vmcnt(10)
	ds_write_b128 v207, v[180:183] offset:9216
	s_waitcnt vmcnt(9)
	ds_write_b128 v207, v[184:187] offset:18432
	s_waitcnt vmcnt(8)
	ds_write_b128 v207, v[188:191] offset:27648
	s_waitcnt lgkmcnt(0)
	v_mfma_f32_16x16x32_bf16 v[136:139], v[214:217], v[222:225], v[136:139]
	s_barrier
	s_setprio 1
	v_mfma_f32_16x16x32_bf16 v[132:135], v[218:221], v[222:225], v[132:135]
	v_mfma_f32_16x16x32_bf16 v[128:131], v[44:47], v[222:225], v[128:131]
	v_mfma_f32_16x16x32_bf16 v[124:127], v[210:213], v[226:229], v[124:127]
	v_mfma_f32_16x16x32_bf16 v[120:123], v[214:217], v[226:229], v[120:123]
	v_mfma_f32_16x16x32_bf16 v[116:119], v[218:221], v[226:229], v[116:119]
	v_mfma_f32_16x16x32_bf16 v[112:115], v[44:47], v[226:229], v[112:115]
	v_mfma_f32_16x16x32_bf16 v[108:111], v[210:213], v[230:233], v[108:111]
	v_mfma_f32_16x16x32_bf16 v[104:107], v[214:217], v[230:233], v[104:107]
	v_mfma_f32_16x16x32_bf16 v[68:71], v[218:221], v[238:241], v[68:71]
	v_mfma_f32_16x16x32_bf16 v[64:67], v[44:47], v[238:241], v[64:67]
	v_mfma_f32_16x16x32_bf16 v[60:63], v[210:213], v[242:245], v[60:63]
	v_mfma_f32_16x16x32_bf16 v[56:59], v[214:217], v[242:245], v[56:59]
	v_mfma_f32_16x16x32_bf16 v[52:55], v[218:221], v[242:245], v[52:55]
	v_mfma_f32_16x16x32_bf16 v[48:51], v[44:47], v[242:245], v[48:51]
	v_mfma_f32_16x16x32_bf16 v[40:43], v[210:213], v[192:195], v[40:43]
	v_mfma_f32_16x16x32_bf16 v[36:39], v[214:217], v[192:195], v[36:39]
	v_mfma_f32_16x16x32_bf16 v[32:35], v[218:221], v[192:195], v[32:35]
	v_mfma_f32_16x16x32_bf16 v[44:47], v[44:47], v[192:195], v[246:249]
	s_cbranch_scc0 .LBB0_1020
	s_cmp_eq_u32 s56, 0
	s_mov_b32 s99, 0x28c4000
	s_cselect_b32 s99, s99, 0x38c4000
	s_lshl_b32 s98, s76, 11
	s_lshl_b32 s100, s75, 1
	s_add_u32 s98, s98, s100
	s_add_u32 s98, s98, s99
	s_add_u32 s100, s34, s98
	s_addc_u32 s101, s35, 0
	v_and_b32_e32 v160, 15, v206
	v_and_b32_e32 v161, 0x80, v201
	v_add_u32_e32 v160, v160, v161
	v_lshlrev_b32_e32 v160, 11, v160
	v_and_b32_e32 v161, 0xc0, v206
	v_lshl_add_u32 v160, v161, 1, v160
	v_and_b32_e32 v161, 4, v201
	v_lshl_add_u32 v160, v161, 3, v160
	v_and_b32_e32 v161, 8, v201
	v_lshl_add_u32 v160, v161, 1, v160
	v_cvt_pk_bf16_f32 v156, v156, v157
	v_cvt_pk_bf16_f32 v157, v158, v159
	v_cvt_pk_bf16_f32 v158, v152, v153
	v_cvt_pk_bf16_f32 v159, v154, v155
	v_cvt_pk_bf16_f32 v148, v148, v149
	v_cvt_pk_bf16_f32 v149, v150, v151
	v_cvt_pk_bf16_f32 v150, v144, v145
	v_cvt_pk_bf16_f32 v151, v146, v147
	v_permlane16_swap_b32_e32 v156, v158
	v_permlane16_swap_b32_e32 v157, v159
	v_permlane16_swap_b32_e32 v148, v150
	v_permlane16_swap_b32_e32 v149, v151
	global_store_dwordx4 v160, v[156:159], s[100:101] sc1
	global_store_dwordx4 v160, v[148:151], s[100:101] offset:64 sc1
	s_add_u32 s100, s100, 0x8000
	s_addc_u32 s101, s101, 0
	v_cvt_pk_bf16_f32 v140, v140, v141
	v_cvt_pk_bf16_f32 v141, v142, v143
	v_cvt_pk_bf16_f32 v142, v136, v137
	v_cvt_pk_bf16_f32 v143, v138, v139
	v_cvt_pk_bf16_f32 v132, v132, v133
	v_cvt_pk_bf16_f32 v133, v134, v135
	v_cvt_pk_bf16_f32 v134, v128, v129
	v_cvt_pk_bf16_f32 v135, v130, v131
	v_permlane16_swap_b32_e32 v140, v142
	v_permlane16_swap_b32_e32 v141, v143
	v_permlane16_swap_b32_e32 v132, v134
	v_permlane16_swap_b32_e32 v133, v135
	global_store_dwordx4 v160, v[140:143], s[100:101] sc1
	global_store_dwordx4 v160, v[132:135], s[100:101] offset:64 sc1
	s_add_u32 s100, s100, 0x8000
	s_addc_u32 s101, s101, 0
	v_cvt_pk_bf16_f32 v124, v124, v125
	v_cvt_pk_bf16_f32 v125, v126, v127
	v_cvt_pk_bf16_f32 v126, v120, v121
	v_cvt_pk_bf16_f32 v127, v122, v123
	v_cvt_pk_bf16_f32 v116, v116, v117
	v_cvt_pk_bf16_f32 v117, v118, v119
	v_cvt_pk_bf16_f32 v118, v112, v113
	v_cvt_pk_bf16_f32 v119, v114, v115
	v_permlane16_swap_b32_e32 v124, v126
	v_permlane16_swap_b32_e32 v125, v127
	v_permlane16_swap_b32_e32 v116, v118
	v_permlane16_swap_b32_e32 v117, v119
	global_store_dwordx4 v160, v[124:127], s[100:101] sc1
	global_store_dwordx4 v160, v[116:119], s[100:101] offset:64 sc1
	s_add_u32 s100, s100, 0x8000
	s_addc_u32 s101, s101, 0
	v_cvt_pk_bf16_f32 v108, v108, v109
	v_cvt_pk_bf16_f32 v109, v110, v111
	v_cvt_pk_bf16_f32 v110, v104, v105
	v_cvt_pk_bf16_f32 v111, v106, v107
	v_cvt_pk_bf16_f32 v100, v100, v101
	v_cvt_pk_bf16_f32 v101, v102, v103
	v_cvt_pk_bf16_f32 v102, v96, v97
	v_cvt_pk_bf16_f32 v103, v98, v99
	v_permlane16_swap_b32_e32 v108, v110
	v_permlane16_swap_b32_e32 v109, v111
	v_permlane16_swap_b32_e32 v100, v102
	v_permlane16_swap_b32_e32 v101, v103
	global_store_dwordx4 v160, v[108:111], s[100:101] sc1
	global_store_dwordx4 v160, v[100:103], s[100:101] offset:64 sc1
	s_add_u32 s100, s100, 0x8000
	s_addc_u32 s101, s101, 0
	v_cvt_pk_bf16_f32 v92, v92, v93
	v_cvt_pk_bf16_f32 v93, v94, v95
	v_cvt_pk_bf16_f32 v94, v88, v89
	v_cvt_pk_bf16_f32 v95, v90, v91
	v_cvt_pk_bf16_f32 v80, v80, v81
	v_cvt_pk_bf16_f32 v81, v82, v83
	v_cvt_pk_bf16_f32 v82, v84, v85
	v_cvt_pk_bf16_f32 v83, v86, v87
	v_permlane16_swap_b32_e32 v92, v94
	v_permlane16_swap_b32_e32 v93, v95
	v_permlane16_swap_b32_e32 v80, v82
	v_permlane16_swap_b32_e32 v81, v83
	global_store_dwordx4 v160, v[92:95], s[100:101] sc1
	global_store_dwordx4 v160, v[80:83], s[100:101] offset:64 sc1
	s_add_u32 s100, s100, 0x8000
	s_addc_u32 s101, s101, 0
	v_cvt_pk_bf16_f32 v76, v76, v77
	v_cvt_pk_bf16_f32 v77, v78, v79
	v_cvt_pk_bf16_f32 v78, v72, v73
	v_cvt_pk_bf16_f32 v79, v74, v75
	v_cvt_pk_bf16_f32 v68, v68, v69
	v_cvt_pk_bf16_f32 v69, v70, v71
	v_cvt_pk_bf16_f32 v70, v64, v65
	v_cvt_pk_bf16_f32 v71, v66, v67
	v_permlane16_swap_b32_e32 v76, v78
	v_permlane16_swap_b32_e32 v77, v79
	v_permlane16_swap_b32_e32 v68, v70
	v_permlane16_swap_b32_e32 v69, v71
	global_store_dwordx4 v160, v[76:79], s[100:101] sc1
	global_store_dwordx4 v160, v[68:71], s[100:101] offset:64 sc1
	s_add_u32 s100, s100, 0x8000
	s_addc_u32 s101, s101, 0
	v_cvt_pk_bf16_f32 v60, v60, v61
	v_cvt_pk_bf16_f32 v61, v62, v63
	v_cvt_pk_bf16_f32 v62, v56, v57
	v_cvt_pk_bf16_f32 v63, v58, v59
	v_cvt_pk_bf16_f32 v52, v52, v53
	v_cvt_pk_bf16_f32 v53, v54, v55
	v_cvt_pk_bf16_f32 v54, v48, v49
	v_cvt_pk_bf16_f32 v55, v50, v51
	v_permlane16_swap_b32_e32 v60, v62
	v_permlane16_swap_b32_e32 v61, v63
	v_permlane16_swap_b32_e32 v52, v54
	v_permlane16_swap_b32_e32 v53, v55
	global_store_dwordx4 v160, v[60:63], s[100:101] sc1
	global_store_dwordx4 v160, v[52:55], s[100:101] offset:64 sc1
	s_add_u32 s100, s100, 0x8000
	s_addc_u32 s101, s101, 0
	v_cvt_pk_bf16_f32 v40, v40, v41
	v_cvt_pk_bf16_f32 v41, v42, v43
	v_cvt_pk_bf16_f32 v42, v36, v37
	v_cvt_pk_bf16_f32 v43, v38, v39
	v_cvt_pk_bf16_f32 v32, v32, v33
	v_cvt_pk_bf16_f32 v33, v34, v35
	v_cvt_pk_bf16_f32 v34, v44, v45
	v_cvt_pk_bf16_f32 v35, v46, v47
	v_permlane16_swap_b32_e32 v40, v42
	v_permlane16_swap_b32_e32 v41, v43
	v_permlane16_swap_b32_e32 v32, v34
	v_permlane16_swap_b32_e32 v33, v35
	global_store_dwordx4 v160, v[40:43], s[100:101] sc1
	global_store_dwordx4 v160, v[32:35], s[100:101] offset:64 sc1
	s_and_b64 vcc, exec, s[50:51]
	s_mov_b32 s56, s48
	s_mov_b32 s75, s74
	s_mov_b32 s76, s73
	s_mov_b64 s[60:61], s[44:45]
	s_mov_b64 s[58:59], s[42:43]
	s_cbranch_vccz .LBB0_1017
	s_load_dwordx16 s[36:51], s[0:1], 0xc0

.LBB0_1146:
	ds_read_b128 v[160:163], v196
	ds_read_b128 v[164:167], v197
	ds_read_b128 v[180:183], v197 offset:64
	ds_read_b128 v[168:171], v196 offset:64
	ds_read_b128 v[172:175], v197 offset:2304
	ds_read_b128 v[206:209], v197 offset:2368
	ds_read_b128 v[176:179], v197 offset:4608
	ds_read_b128 v[210:213], v197 offset:4672
	ds_read_b128 v[184:187], v197 offset:6912
	ds_read_b128 v[214:217], v197 offset:6976
	s_waitcnt lgkmcnt(8)
	v_mfma_f32_16x16x32_bf16 v[156:159], v[164:167], v[160:163], v[156:159]
	s_add_i32 s41, s41, 2
	s_add_u32 s42, s39, 0xffffff80
	s_addc_u32 s43, s40, -1
	s_waitcnt lgkmcnt(5)
	v_mfma_f32_16x16x32_bf16 v[152:155], v[172:175], v[160:163], v[152:155]
	s_add_u32 s44, s26, 0xffffff80
	s_addc_u32 s45, s27, -1
	s_cmp_gt_u32 s41, 13
	s_waitcnt lgkmcnt(3)
	v_mfma_f32_16x16x32_bf16 v[148:151], v[176:179], v[160:163], v[148:151]
	s_cselect_b64 s[4:5], -1, 0
	s_and_b64 vcc, s[4:5], exec
	s_cselect_b32 s5, s11, s43
	s_waitcnt lgkmcnt(1)
	v_mfma_f32_16x16x32_bf16 v[144:147], v[184:187], v[160:163], v[144:147]
	ds_read_b128 v[160:163], v196 offset:2304
	ds_read_b128 v[188:191], v196 offset:2368
	s_cselect_b32 s4, s10, s42
	s_cselect_b32 s43, s13, s45
	s_waitcnt lgkmcnt(1)
	v_mfma_f32_16x16x32_bf16 v[140:143], v[164:167], v[160:163], v[140:143]
	s_cselect_b32 s42, s12, s44
	s_cmp_gt_u32 s41, 12
	v_mfma_f32_16x16x32_bf16 v[136:139], v[172:175], v[160:163], v[136:139]
	v_mfma_f32_16x16x32_bf16 v[132:135], v[176:179], v[160:163], v[132:135]
	v_mfma_f32_16x16x32_bf16 v[128:131], v[184:187], v[160:163], v[128:131]
	ds_read_b128 v[160:163], v196 offset:4608
	ds_read_b128 v[218:221], v196 offset:4672
	s_waitcnt lgkmcnt(1)
	v_mfma_f32_16x16x32_bf16 v[124:127], v[164:167], v[160:163], v[124:127]
	v_mfma_f32_16x16x32_bf16 v[120:123], v[172:175], v[160:163], v[120:123]
	v_mfma_f32_16x16x32_bf16 v[116:119], v[176:179], v[160:163], v[116:119]
	v_mfma_f32_16x16x32_bf16 v[112:115], v[184:187], v[160:163], v[112:115]
	ds_read_b128 v[160:163], v196 offset:6912
	ds_read_b128 v[222:225], v196 offset:6976
	s_waitcnt lgkmcnt(1)
	v_mfma_f32_16x16x32_bf16 v[108:111], v[164:167], v[160:163], v[108:111]
	v_mfma_f32_16x16x32_bf16 v[104:107], v[172:175], v[160:163], v[104:107]
	v_mfma_f32_16x16x32_bf16 v[100:103], v[176:179], v[160:163], v[100:103]
	v_mfma_f32_16x16x32_bf16 v[96:99], v[184:187], v[160:163], v[96:99]
	ds_read_b128 v[160:163], v196 offset:9216
	ds_read_b128 v[226:229], v196 offset:9280
	s_waitcnt lgkmcnt(1)
	v_mfma_f32_16x16x32_bf16 v[92:95], v[164:167], v[160:163], v[92:95]
	v_mfma_f32_16x16x32_bf16 v[88:91], v[172:175], v[160:163], v[88:91]
	v_mfma_f32_16x16x32_bf16 v[84:87], v[176:179], v[160:163], v[84:87]
	v_mfma_f32_16x16x32_bf16 v[80:83], v[184:187], v[160:163], v[80:83]
	ds_read_b128 v[160:163], v196 offset:11520
	ds_read_b128 v[230:233], v196 offset:11584
	s_waitcnt lgkmcnt(1)
	v_mfma_f32_16x16x32_bf16 v[76:79], v[164:167], v[160:163], v[76:79]
	v_mfma_f32_16x16x32_bf16 v[72:75], v[172:175], v[160:163], v[72:75]
	v_mfma_f32_16x16x32_bf16 v[68:71], v[176:179], v[160:163], v[68:71]
	v_mfma_f32_16x16x32_bf16 v[64:67], v[184:187], v[160:163], v[64:67]
	ds_read_b128 v[160:163], v196 offset:13824
	ds_read_b128 v[234:237], v196 offset:13888
	s_waitcnt lgkmcnt(1)
	v_mfma_f32_16x16x32_bf16 v[60:63], v[164:167], v[160:163], v[60:63]
	v_mfma_f32_16x16x32_bf16 v[56:59], v[172:175], v[160:163], v[56:59]
	v_mfma_f32_16x16x32_bf16 v[52:55], v[176:179], v[160:163], v[52:55]
	v_mfma_f32_16x16x32_bf16 v[48:51], v[184:187], v[160:163], v[48:51]
	ds_read_b128 v[160:163], v196 offset:16128
	ds_read_b128 v[238:241], v196 offset:16192
	s_setprio 0
	s_waitcnt vmcnt(6)
	ds_write_b128 v194, v[4:7] offset:36864
	s_waitcnt vmcnt(5)
	ds_write_b128 v194, v[8:11] offset:46080
	s_waitcnt vmcnt(4)
	ds_write_b128 v194, v[12:15] offset:55296
	s_waitcnt vmcnt(3)
	ds_write_b128 v194, v[16:19] offset:64512
	s_waitcnt vmcnt(3)
	ds_write_b128 v199, v[0:3]
	s_waitcnt vmcnt(2)
	ds_write_b128 v199, v[20:23] offset:9216
	v_mfma_f32_16x16x32_bf16 v[20:23], v[214:217], v[226:229], v[80:83]
	s_waitcnt vmcnt(1)
	ds_write_b128 v199, v[24:27] offset:18432
	s_waitcnt vmcnt(0)
	ds_write_b128 v199, v[28:31] offset:27648
	v_lshl_add_u64 v[80:81], s[4:5], 0, v[192:193]
	v_mfma_f32_16x16x32_bf16 v[24:27], v[180:183], v[230:233], v[76:79]
	v_lshl_add_u64 v[82:83], s[42:43], 0, v[192:193]
	s_cselect_b32 s43, s38, s27
	s_cselect_b32 s42, s37, s26
	v_add_co_u32_e64 v76, s[4:5], s23, v80
	v_mfma_f32_16x16x32_bf16 v[28:31], v[206:209], v[230:233], v[72:75]
	s_nop 0
	v_addc_co_u32_e64 v77, s[4:5], 0, v81, s[4:5]
	s_nop 0
	v_add_co_u32_e64 v72, s[4:5], s25, v80
	s_waitcnt lgkmcnt(9)
	v_mfma_f32_16x16x32_bf16 v[36:39], v[164:167], v[160:163], v[36:39]
	v_addc_co_u32_e64 v73, s[4:5], 0, v81, s[4:5]
	v_add_co_u32_e64 v74, s[4:5], s30, v80
	v_mfma_f32_16x16x32_bf16 v[32:35], v[172:175], v[160:163], v[32:35]
	s_nop 0
	v_addc_co_u32_e64 v75, s[4:5], 0, v81, s[4:5]
	v_add_co_u32_e64 v78, s[4:5], s23, v82
	v_mfma_f32_16x16x32_bf16 v[44:47], v[176:179], v[160:163], v[44:47]
	s_nop 0
	v_addc_co_u32_e64 v79, s[4:5], 0, v83, s[4:5]
	global_load_dwordx4 v[164:167], v[82:83], off
	v_mfma_f32_16x16x32_bf16 v[40:43], v[184:187], v[160:163], v[40:43]
	global_load_dwordx4 v[160:163], v[80:81], off
	v_add_co_u32_e64 v80, s[4:5], s25, v82
	v_mfma_f32_16x16x32_bf16 v[156:159], v[180:183], v[168:171], v[156:159]
	s_nop 0
	v_addc_co_u32_e64 v81, s[4:5], 0, v83, s[4:5]
	v_add_co_u32_e64 v82, s[4:5], s30, v82
	v_mfma_f32_16x16x32_bf16 v[152:155], v[206:209], v[168:171], v[152:155]
	s_nop 0
	v_addc_co_u32_e64 v83, s[4:5], 0, v83, s[4:5]
	s_cselect_b32 s5, s21, s40
	v_mfma_f32_16x16x32_bf16 v[148:151], v[210:213], v[168:171], v[148:151]
	s_cselect_b32 s4, s19, s39
	s_add_u32 s26, s26, 0x100
	s_addc_u32 s27, s27, 0
	v_mfma_f32_16x16x32_bf16 v[144:147], v[214:217], v[168:171], v[144:147]
	global_load_dwordx4 v[168:171], v[76:77], off
	global_load_dwordx4 v[172:175], v[72:73], off
	global_load_dwordx4 v[176:179], v[74:75], off
	s_add_u32 s39, s39, 0x100
	s_addc_u32 s40, s40, 0
	v_mfma_f32_16x16x32_bf16 v[140:143], v[180:183], v[188:191], v[140:143]
	v_mfma_f32_16x16x32_bf16 v[136:139], v[206:209], v[188:191], v[136:139]
	v_mfma_f32_16x16x32_bf16 v[132:135], v[210:213], v[188:191], v[132:135]
	v_mfma_f32_16x16x32_bf16 v[128:131], v[214:217], v[188:191], v[128:131]
	v_mfma_f32_16x16x32_bf16 v[124:127], v[180:183], v[218:221], v[124:127]
	v_mfma_f32_16x16x32_bf16 v[108:111], v[180:183], v[222:225], v[108:111]
	v_mfma_f32_16x16x32_bf16 v[8:11], v[180:183], v[226:229], v[92:95]
	v_mfma_f32_16x16x32_bf16 v[60:63], v[180:183], v[234:237], v[60:63]
	s_waitcnt lgkmcnt(8)
	v_mfma_f32_16x16x32_bf16 v[36:39], v[180:183], v[238:241], v[36:39]
	global_load_dwordx4 v[180:183], v[78:79], off
	global_load_dwordx4 v[184:187], v[80:81], off
	global_load_dwordx4 v[188:191], v[82:83], off
	s_waitcnt lgkmcnt(0)
	s_barrier
	s_setprio 1
	ds_read_b128 v[76:79], v196 offset:36864
	v_mfma_f32_16x16x32_bf16 v[120:123], v[206:209], v[218:221], v[120:123]
	v_mfma_f32_16x16x32_bf16 v[116:119], v[210:213], v[218:221], v[116:119]
	v_mfma_f32_16x16x32_bf16 v[104:107], v[206:209], v[222:225], v[104:107]
	v_mfma_f32_16x16x32_bf16 v[4:7], v[210:213], v[222:225], v[100:103]
	v_mfma_f32_16x16x32_bf16 v[0:3], v[214:217], v[222:225], v[96:99]
	v_mfma_f32_16x16x32_bf16 v[12:15], v[206:209], v[226:229], v[88:91]
	v_mfma_f32_16x16x32_bf16 v[16:19], v[210:213], v[226:229], v[84:87]
	v_mfma_f32_16x16x32_bf16 v[68:71], v[210:213], v[230:233], v[68:71]
	v_mfma_f32_16x16x32_bf16 v[56:59], v[206:209], v[234:237], v[56:59]
	v_mfma_f32_16x16x32_bf16 v[52:55], v[210:213], v[234:237], v[52:55]
	v_mfma_f32_16x16x32_bf16 v[32:35], v[206:209], v[238:241], v[32:35]
	ds_read_b128 v[84:87], v200
	ds_read_b128 v[206:209], v200 offset:64
	ds_read_b128 v[88:91], v196 offset:36928
	v_mfma_f32_16x16x32_bf16 v[72:75], v[210:213], v[238:241], v[44:47]
	ds_read_b128 v[96:99], v200 offset:2304
	ds_read_b128 v[210:213], v200 offset:2368
	v_mfma_f32_16x16x32_bf16 v[80:83], v[214:217], v[238:241], v[40:43]
	s_waitcnt lgkmcnt(4)
	v_mfma_f32_16x16x32_bf16 v[92:95], v[84:87], v[76:79], v[156:159]
	s_waitcnt lgkmcnt(1)
	v_mfma_f32_16x16x32_bf16 v[100:103], v[96:99], v[76:79], v[152:155]
	s_nop 2
	ds_read_b128 v[152:155], v200 offset:4608
	ds_read_b128 v[44:47], v200 offset:4672
	ds_read_b128 v[156:159], v200 offset:6912
	ds_read_b128 v[40:43], v200 offset:6976
	v_mfma_f32_16x16x32_bf16 v[112:115], v[214:217], v[218:221], v[112:115]
	v_mfma_f32_16x16x32_bf16 v[64:67], v[214:217], v[230:233], v[64:67]
	v_mfma_f32_16x16x32_bf16 v[48:51], v[214:217], v[234:237], v[48:51]
	s_waitcnt lgkmcnt(3)
	v_mfma_f32_16x16x32_bf16 v[148:151], v[152:155], v[76:79], v[148:151]
	s_waitcnt lgkmcnt(1)
	v_mfma_f32_16x16x32_bf16 v[76:79], v[156:159], v[76:79], v[144:147]
	s_nop 2
	ds_read_b128 v[144:147], v196 offset:39168
	ds_read_b128 v[214:217], v196 offset:39232
	s_waitcnt lgkmcnt(1)
	v_mfma_f32_16x16x32_bf16 v[140:143], v[84:87], v[144:147], v[140:143]
	v_mfma_f32_16x16x32_bf16 v[136:139], v[96:99], v[144:147], v[136:139]
	v_mfma_f32_16x16x32_bf16 v[132:135], v[152:155], v[144:147], v[132:135]
	v_mfma_f32_16x16x32_bf16 v[128:131], v[156:159], v[144:147], v[128:131]
	ds_read_b128 v[144:147], v196 offset:41472
	ds_read_b128 v[218:221], v196 offset:41536
	s_waitcnt lgkmcnt(1)
	v_mfma_f32_16x16x32_bf16 v[124:127], v[84:87], v[144:147], v[124:127]
	v_mfma_f32_16x16x32_bf16 v[120:123], v[96:99], v[144:147], v[120:123]
	v_mfma_f32_16x16x32_bf16 v[116:119], v[152:155], v[144:147], v[116:119]
	v_mfma_f32_16x16x32_bf16 v[112:115], v[156:159], v[144:147], v[112:115]
	ds_read_b128 v[144:147], v196 offset:43776
	ds_read_b128 v[222:225], v196 offset:43840
	s_waitcnt lgkmcnt(1)
	v_mfma_f32_16x16x32_bf16 v[108:111], v[84:87], v[144:147], v[108:111]
	v_mfma_f32_16x16x32_bf16 v[104:107], v[96:99], v[144:147], v[104:107]
	v_mfma_f32_16x16x32_bf16 v[4:7], v[152:155], v[144:147], v[4:7]
	v_mfma_f32_16x16x32_bf16 v[0:3], v[156:159], v[144:147], v[0:3]
	ds_read_b128 v[144:147], v196 offset:46080
	ds_read_b128 v[226:229], v196 offset:46144
	s_waitcnt lgkmcnt(1)
	v_mfma_f32_16x16x32_bf16 v[8:11], v[84:87], v[144:147], v[8:11]
	v_mfma_f32_16x16x32_bf16 v[12:15], v[96:99], v[144:147], v[12:15]
	v_mfma_f32_16x16x32_bf16 v[16:19], v[152:155], v[144:147], v[16:19]
	v_mfma_f32_16x16x32_bf16 v[20:23], v[156:159], v[144:147], v[20:23]
	ds_read_b128 v[144:147], v196 offset:48384
	ds_read_b128 v[230:233], v196 offset:48448
	s_waitcnt lgkmcnt(1)
	v_mfma_f32_16x16x32_bf16 v[24:27], v[84:87], v[144:147], v[24:27]
	v_mfma_f32_16x16x32_bf16 v[28:31], v[96:99], v[144:147], v[28:31]
	v_mfma_f32_16x16x32_bf16 v[68:71], v[152:155], v[144:147], v[68:71]
	v_mfma_f32_16x16x32_bf16 v[64:67], v[156:159], v[144:147], v[64:67]
	ds_read_b128 v[144:147], v196 offset:50688
	ds_read_b128 v[234:237], v196 offset:50752
	s_waitcnt lgkmcnt(1)
	v_mfma_f32_16x16x32_bf16 v[60:63], v[84:87], v[144:147], v[60:63]
	v_mfma_f32_16x16x32_bf16 v[56:59], v[96:99], v[144:147], v[56:59]
	v_mfma_f32_16x16x32_bf16 v[52:55], v[152:155], v[144:147], v[52:55]
	v_mfma_f32_16x16x32_bf16 v[48:51], v[156:159], v[144:147], v[48:51]
	ds_read_b128 v[144:147], v196 offset:52992
	ds_read_b128 v[238:241], v196 offset:53056
	s_waitcnt lgkmcnt(1)
	v_mfma_f32_16x16x32_bf16 v[242:245], v[152:155], v[144:147], v[72:75]
	v_mfma_f32_16x16x32_bf16 v[152:155], v[210:213], v[88:91], v[100:103]
	v_mfma_f32_16x16x32_bf16 v[100:103], v[44:47], v[222:225], v[4:7]
	s_nop 2
	v_lshl_add_u64 v[4:5], s[4:5], 0, v[192:193]
	v_mfma_f32_16x16x32_bf16 v[246:249], v[156:159], v[144:147], v[80:83]
	v_lshl_add_u64 v[6:7], s[42:43], 0, v[192:193]
	v_mfma_f32_16x16x32_bf16 v[156:159], v[206:209], v[88:91], v[92:95]
	v_mfma_f32_16x16x32_bf16 v[92:95], v[206:209], v[226:229], v[8:11]
	s_nop 2
	v_add_co_u32_e64 v8, s[4:5], s23, v4
	v_mfma_f32_16x16x32_bf16 v[36:39], v[84:87], v[144:147], v[36:39]
	s_nop 0
	v_addc_co_u32_e64 v9, s[4:5], 0, v5, s[4:5]
	v_mfma_f32_16x16x32_bf16 v[32:35], v[96:99], v[144:147], v[32:35]
	v_mfma_f32_16x16x32_bf16 v[148:151], v[44:47], v[88:91], v[148:151]
	v_mfma_f32_16x16x32_bf16 v[144:147], v[40:43], v[88:91], v[76:79]
	v_mfma_f32_16x16x32_bf16 v[88:91], v[210:213], v[226:229], v[12:15]
	s_nop 2
	v_add_co_u32_e64 v12, s[4:5], s25, v4
	v_mfma_f32_16x16x32_bf16 v[84:87], v[44:47], v[226:229], v[16:19]
	s_nop 0
	v_addc_co_u32_e64 v13, s[4:5], 0, v5, s[4:5]
	s_nop 0
	v_add_co_u32_e64 v16, s[4:5], s30, v4
	v_mfma_f32_16x16x32_bf16 v[80:83], v[40:43], v[226:229], v[20:23]
	s_nop 0
	v_addc_co_u32_e64 v17, s[4:5], 0, v5, s[4:5]
	s_nop 0
	v_add_co_u32_e64 v20, s[4:5], s23, v6
	v_mfma_f32_16x16x32_bf16 v[76:79], v[206:209], v[230:233], v[24:27]
	s_nop 0
	v_addc_co_u32_e64 v21, s[4:5], 0, v7, s[4:5]
	s_nop 0
	v_add_co_u32_e64 v24, s[4:5], s25, v6
	v_mfma_f32_16x16x32_bf16 v[72:75], v[210:213], v[230:233], v[28:31]
	s_nop 0
	v_addc_co_u32_e64 v25, s[4:5], 0, v7, s[4:5]
	s_nop 0
	v_add_co_u32_e64 v28, s[4:5], s30, v6
	v_mfma_f32_16x16x32_bf16 v[96:99], v[40:43], v[222:225], v[0:3]
	s_nop 0
	v_addc_co_u32_e64 v29, s[4:5], 0, v7, s[4:5]
	s_nop 0
	global_load_dwordx4 v[0:3], v[6:7], off
	s_nop 0
	global_load_dwordx4 v[4:7], v[4:5], off
	s_nop 0
	global_load_dwordx4 v[8:11], v[8:9], off
	s_nop 0
	global_load_dwordx4 v[12:15], v[12:13], off
	s_nop 0
	global_load_dwordx4 v[16:19], v[16:17], off
	s_nop 0
	global_load_dwordx4 v[20:23], v[20:21], off
	s_nop 0
	global_load_dwordx4 v[24:27], v[24:25], off
	v_mfma_f32_16x16x32_bf16 v[140:143], v[206:209], v[214:217], v[140:143]
	global_load_dwordx4 v[28:31], v[28:29], off
	s_setprio 0
	s_waitcnt vmcnt(14)
	ds_write_b128 v194, v[160:163]
	ds_write_b128 v195, v[164:167]
	s_waitcnt vmcnt(13)
	ds_write_b128 v194, v[168:171] offset:9216
	s_waitcnt vmcnt(12)
	ds_write_b128 v194, v[172:175] offset:18432
	s_waitcnt vmcnt(11)
	ds_write_b128 v194, v[176:179] offset:27648
	s_waitcnt vmcnt(10)
	ds_write_b128 v195, v[180:183] offset:9216
	s_waitcnt vmcnt(9)
	ds_write_b128 v195, v[184:187] offset:18432
	s_waitcnt vmcnt(8)
	ds_write_b128 v195, v[188:191] offset:27648
	s_waitcnt lgkmcnt(0)
	v_mfma_f32_16x16x32_bf16 v[136:139], v[210:213], v[214:217], v[136:139]
	s_barrier
	s_setprio 1
	v_mfma_f32_16x16x32_bf16 v[132:135], v[44:47], v[214:217], v[132:135]
	v_mfma_f32_16x16x32_bf16 v[128:131], v[40:43], v[214:217], v[128:131]
	v_mfma_f32_16x16x32_bf16 v[124:127], v[206:209], v[218:221], v[124:127]
	v_mfma_f32_16x16x32_bf16 v[120:123], v[210:213], v[218:221], v[120:123]
	v_mfma_f32_16x16x32_bf16 v[116:119], v[44:47], v[218:221], v[116:119]
	v_mfma_f32_16x16x32_bf16 v[112:115], v[40:43], v[218:221], v[112:115]
	v_mfma_f32_16x16x32_bf16 v[108:111], v[206:209], v[222:225], v[108:111]
	v_mfma_f32_16x16x32_bf16 v[104:107], v[210:213], v[222:225], v[104:107]
	v_mfma_f32_16x16x32_bf16 v[68:71], v[44:47], v[230:233], v[68:71]
	v_mfma_f32_16x16x32_bf16 v[64:67], v[40:43], v[230:233], v[64:67]
	v_mfma_f32_16x16x32_bf16 v[60:63], v[206:209], v[234:237], v[60:63]
	v_mfma_f32_16x16x32_bf16 v[56:59], v[210:213], v[234:237], v[56:59]
	v_mfma_f32_16x16x32_bf16 v[52:55], v[44:47], v[234:237], v[52:55]
	v_mfma_f32_16x16x32_bf16 v[48:51], v[40:43], v[234:237], v[48:51]
	v_mfma_f32_16x16x32_bf16 v[36:39], v[206:209], v[238:241], v[36:39]
	v_mfma_f32_16x16x32_bf16 v[32:35], v[210:213], v[238:241], v[32:35]
	v_mfma_f32_16x16x32_bf16 v[44:47], v[44:47], v[238:241], v[242:245]
	v_mfma_f32_16x16x32_bf16 v[40:43], v[40:43], v[238:241], v[246:249]
	s_cbranch_vccz .LBB0_1146
	s_mul_i32 s98, s22, 0x1600
	s_add_u32 s98, s98, s24
	s_add_u32 s100, s8, s98
	s_addc_u32 s101, s9, 0
	v_and_b32_e32 v168, 15, v198
	v_and_b32_e32 v169, 0x80, v201
	v_add_u32_e32 v168, v168, v169
	v_mul_u32_u24_e32 v168, 0x1600, v168
	v_and_b32_e32 v169, 0xc0, v198
	v_add_u32_e32 v168, v168, v169
	v_and_b32_e32 v169, 4, v201
	v_lshl_add_u32 v168, v169, 3, v168
	v_and_b32_e32 v169, 8, v201
	v_lshl_add_u32 v168, v169, 1, v168
	v_mul_f32_e32 v160, 0xbfb8aa3b, v156
	v_mul_f32_e32 v161, 0xbfb8aa3b, v157
	v_mul_f32_e32 v162, 0xbfb8aa3b, v158
	v_mul_f32_e32 v163, 0xbfb8aa3b, v159
	v_mul_f32_e32 v164, 0xbfb8aa3b, v148
	v_mul_f32_e32 v165, 0xbfb8aa3b, v149
	v_mul_f32_e32 v166, 0xbfb8aa3b, v150
	v_mul_f32_e32 v167, 0xbfb8aa3b, v151
	v_exp_f32_e32 v160, v160
	v_exp_f32_e32 v161, v161
	v_exp_f32_e32 v162, v162
	v_exp_f32_e32 v163, v163
	v_exp_f32_e32 v164, v164
	v_exp_f32_e32 v165, v165
	v_exp_f32_e32 v166, v166
	v_exp_f32_e32 v167, v167
	v_add_f32_e32 v160, 1.0, v160
	v_add_f32_e32 v161, 1.0, v161
	v_add_f32_e32 v162, 1.0, v162
	v_add_f32_e32 v163, 1.0, v163
	v_add_f32_e32 v164, 1.0, v164
	v_add_f32_e32 v165, 1.0, v165
	v_add_f32_e32 v166, 1.0, v166
	v_add_f32_e32 v167, 1.0, v167
	v_rcp_f32_e32 v160, v160
	v_rcp_f32_e32 v161, v161
	v_rcp_f32_e32 v162, v162
	v_rcp_f32_e32 v163, v163
	v_rcp_f32_e32 v164, v164
	v_rcp_f32_e32 v165, v165
	v_rcp_f32_e32 v166, v166
	v_rcp_f32_e32 v167, v167
	v_mul_f32_e32 v156, v156, v160
	v_mul_f32_e32 v157, v157, v161
	v_mul_f32_e32 v158, v158, v162
	v_mul_f32_e32 v159, v159, v163
	v_mul_f32_e32 v148, v148, v164
	v_mul_f32_e32 v149, v149, v165
	v_mul_f32_e32 v150, v150, v166
	v_mul_f32_e32 v151, v151, v167
	v_mul_f32_e32 v152, v156, v152
	v_mul_f32_e32 v153, v157, v153
	v_mul_f32_e32 v154, v158, v154
	v_mul_f32_e32 v155, v159, v155
	v_mul_f32_e32 v144, v148, v144
	v_mul_f32_e32 v145, v149, v145
	v_mul_f32_e32 v146, v150, v146
	v_mul_f32_e32 v147, v151, v147
	v_cvt_pk_bf16_f32 v156, v152, v153
	v_cvt_pk_bf16_f32 v157, v154, v155
	v_cvt_pk_bf16_f32 v158, v144, v145
	v_cvt_pk_bf16_f32 v159, v146, v147
	s_nop 1
	v_permlane16_swap_b32_e32 v156, v158
	v_permlane16_swap_b32_e32 v157, v159
	global_store_dwordx4 v168, v[156:159], s[100:101] sc1
	s_add_u32 s100, s100, 0x16000
	s_addc_u32 s101, s101, 0
	v_mul_f32_e32 v160, 0xbfb8aa3b, v140
	v_mul_f32_e32 v161, 0xbfb8aa3b, v141
	v_mul_f32_e32 v162, 0xbfb8aa3b, v142
	v_mul_f32_e32 v163, 0xbfb8aa3b, v143
	v_mul_f32_e32 v164, 0xbfb8aa3b, v132
	v_mul_f32_e32 v165, 0xbfb8aa3b, v133
	v_mul_f32_e32 v166, 0xbfb8aa3b, v134
	v_mul_f32_e32 v167, 0xbfb8aa3b, v135
	v_exp_f32_e32 v160, v160
	v_exp_f32_e32 v161, v161
	v_exp_f32_e32 v162, v162
	v_exp_f32_e32 v163, v163
	v_exp_f32_e32 v164, v164
	v_exp_f32_e32 v165, v165
	v_exp_f32_e32 v166, v166
	v_exp_f32_e32 v167, v167
	v_add_f32_e32 v160, 1.0, v160
	v_add_f32_e32 v161, 1.0, v161
	v_add_f32_e32 v162, 1.0, v162
	v_add_f32_e32 v163, 1.0, v163
	v_add_f32_e32 v164, 1.0, v164
	v_add_f32_e32 v165, 1.0, v165
	v_add_f32_e32 v166, 1.0, v166
	v_add_f32_e32 v167, 1.0, v167
	v_rcp_f32_e32 v160, v160
	v_rcp_f32_e32 v161, v161
	v_rcp_f32_e32 v162, v162
	v_rcp_f32_e32 v163, v163
	v_rcp_f32_e32 v164, v164
	v_rcp_f32_e32 v165, v165
	v_rcp_f32_e32 v166, v166
	v_rcp_f32_e32 v167, v167
	v_mul_f32_e32 v140, v140, v160
	v_mul_f32_e32 v141, v141, v161
	v_mul_f32_e32 v142, v142, v162
	v_mul_f32_e32 v143, v143, v163
	v_mul_f32_e32 v132, v132, v164
	v_mul_f32_e32 v133, v133, v165
	v_mul_f32_e32 v134, v134, v166
	v_mul_f32_e32 v135, v135, v167
	v_mul_f32_e32 v136, v140, v136
	v_mul_f32_e32 v137, v141, v137
	v_mul_f32_e32 v138, v142, v138
	v_mul_f32_e32 v139, v143, v139
	v_mul_f32_e32 v128, v132, v128
	v_mul_f32_e32 v129, v133, v129
	v_mul_f32_e32 v130, v134, v130
	v_mul_f32_e32 v131, v135, v131
	v_cvt_pk_bf16_f32 v140, v136, v137
	v_cvt_pk_bf16_f32 v141, v138, v139
	v_cvt_pk_bf16_f32 v142, v128, v129
	v_cvt_pk_bf16_f32 v143, v130, v131
	s_nop 1
	v_permlane16_swap_b32_e32 v140, v142
	v_permlane16_swap_b32_e32 v141, v143
	global_store_dwordx4 v168, v[140:143], s[100:101] sc1
	s_add_u32 s100, s100, 0x16000
	s_addc_u32 s101, s101, 0
	v_mul_f32_e32 v160, 0xbfb8aa3b, v124
	v_mul_f32_e32 v161, 0xbfb8aa3b, v125
	v_mul_f32_e32 v162, 0xbfb8aa3b, v126
	v_mul_f32_e32 v163, 0xbfb8aa3b, v127
	v_mul_f32_e32 v164, 0xbfb8aa3b, v116
	v_mul_f32_e32 v165, 0xbfb8aa3b, v117
	v_mul_f32_e32 v166, 0xbfb8aa3b, v118
	v_mul_f32_e32 v167, 0xbfb8aa3b, v119
	v_exp_f32_e32 v160, v160
	v_exp_f32_e32 v161, v161
	v_exp_f32_e32 v162, v162
	v_exp_f32_e32 v163, v163
	v_exp_f32_e32 v164, v164
	v_exp_f32_e32 v165, v165
	v_exp_f32_e32 v166, v166
	v_exp_f32_e32 v167, v167
	v_add_f32_e32 v160, 1.0, v160
	v_add_f32_e32 v161, 1.0, v161
	v_add_f32_e32 v162, 1.0, v162
	v_add_f32_e32 v163, 1.0, v163
	v_add_f32_e32 v164, 1.0, v164
	v_add_f32_e32 v165, 1.0, v165
	v_add_f32_e32 v166, 1.0, v166
	v_add_f32_e32 v167, 1.0, v167
	v_rcp_f32_e32 v160, v160
	v_rcp_f32_e32 v161, v161
	v_rcp_f32_e32 v162, v162
	v_rcp_f32_e32 v163, v163
	v_rcp_f32_e32 v164, v164
	v_rcp_f32_e32 v165, v165
	v_rcp_f32_e32 v166, v166
	v_rcp_f32_e32 v167, v167
	v_mul_f32_e32 v124, v124, v160
	v_mul_f32_e32 v125, v125, v161
	v_mul_f32_e32 v126, v126, v162
	v_mul_f32_e32 v127, v127, v163
	v_mul_f32_e32 v116, v116, v164
	v_mul_f32_e32 v117, v117, v165
	v_mul_f32_e32 v118, v118, v166
	v_mul_f32_e32 v119, v119, v167
	v_mul_f32_e32 v120, v124, v120
	v_mul_f32_e32 v121, v125, v121
	v_mul_f32_e32 v122, v126, v122
	v_mul_f32_e32 v123, v127, v123
	v_mul_f32_e32 v112, v116, v112
	v_mul_f32_e32 v113, v117, v113
	v_mul_f32_e32 v114, v118, v114
	v_mul_f32_e32 v115, v119, v115
	v_cvt_pk_bf16_f32 v124, v120, v121
	v_cvt_pk_bf16_f32 v125, v122, v123
	v_cvt_pk_bf16_f32 v126, v112, v113
	v_cvt_pk_bf16_f32 v127, v114, v115
	s_nop 1
	v_permlane16_swap_b32_e32 v124, v126
	v_permlane16_swap_b32_e32 v125, v127
	global_store_dwordx4 v168, v[124:127], s[100:101] sc1
	s_add_u32 s100, s100, 0x16000
	s_addc_u32 s101, s101, 0
	v_mul_f32_e32 v160, 0xbfb8aa3b, v108
	v_mul_f32_e32 v161, 0xbfb8aa3b, v109
	v_mul_f32_e32 v162, 0xbfb8aa3b, v110
	v_mul_f32_e32 v163, 0xbfb8aa3b, v111
	v_mul_f32_e32 v164, 0xbfb8aa3b, v100
	v_mul_f32_e32 v165, 0xbfb8aa3b, v101
	v_mul_f32_e32 v166, 0xbfb8aa3b, v102
	v_mul_f32_e32 v167, 0xbfb8aa3b, v103
	v_exp_f32_e32 v160, v160
	v_exp_f32_e32 v161, v161
	v_exp_f32_e32 v162, v162
	v_exp_f32_e32 v163, v163
	v_exp_f32_e32 v164, v164
	v_exp_f32_e32 v165, v165
	v_exp_f32_e32 v166, v166
	v_exp_f32_e32 v167, v167
	v_add_f32_e32 v160, 1.0, v160
	v_add_f32_e32 v161, 1.0, v161
	v_add_f32_e32 v162, 1.0, v162
	v_add_f32_e32 v163, 1.0, v163
	v_add_f32_e32 v164, 1.0, v164
	v_add_f32_e32 v165, 1.0, v165
	v_add_f32_e32 v166, 1.0, v166
	v_add_f32_e32 v167, 1.0, v167
	v_rcp_f32_e32 v160, v160
	v_rcp_f32_e32 v161, v161
	v_rcp_f32_e32 v162, v162
	v_rcp_f32_e32 v163, v163
	v_rcp_f32_e32 v164, v164
	v_rcp_f32_e32 v165, v165
	v_rcp_f32_e32 v166, v166
	v_rcp_f32_e32 v167, v167
	v_mul_f32_e32 v108, v108, v160
	v_mul_f32_e32 v109, v109, v161
	v_mul_f32_e32 v110, v110, v162
	v_mul_f32_e32 v111, v111, v163
	v_mul_f32_e32 v100, v100, v164
	v_mul_f32_e32 v101, v101, v165
	v_mul_f32_e32 v102, v102, v166
	v_mul_f32_e32 v103, v103, v167
	v_mul_f32_e32 v104, v108, v104
	v_mul_f32_e32 v105, v109, v105
	v_mul_f32_e32 v106, v110, v106
	v_mul_f32_e32 v107, v111, v107
	v_mul_f32_e32 v96, v100, v96
	v_mul_f32_e32 v97, v101, v97
	v_mul_f32_e32 v98, v102, v98
	v_mul_f32_e32 v99, v103, v99
	v_cvt_pk_bf16_f32 v108, v104, v105
	v_cvt_pk_bf16_f32 v109, v106, v107
	v_cvt_pk_bf16_f32 v110, v96, v97
	v_cvt_pk_bf16_f32 v111, v98, v99
	s_nop 1
	v_permlane16_swap_b32_e32 v108, v110
	v_permlane16_swap_b32_e32 v109, v111
	global_store_dwordx4 v168, v[108:111], s[100:101] sc1
	s_add_u32 s100, s100, 0x16000
	s_addc_u32 s101, s101, 0
	v_mul_f32_e32 v160, 0xbfb8aa3b, v92
	v_mul_f32_e32 v161, 0xbfb8aa3b, v93
	v_mul_f32_e32 v162, 0xbfb8aa3b, v94
	v_mul_f32_e32 v163, 0xbfb8aa3b, v95
	v_mul_f32_e32 v164, 0xbfb8aa3b, v84
	v_mul_f32_e32 v165, 0xbfb8aa3b, v85
	v_mul_f32_e32 v166, 0xbfb8aa3b, v86
	v_mul_f32_e32 v167, 0xbfb8aa3b, v87
	v_exp_f32_e32 v160, v160
	v_exp_f32_e32 v161, v161
	v_exp_f32_e32 v162, v162
	v_exp_f32_e32 v163, v163
	v_exp_f32_e32 v164, v164
	v_exp_f32_e32 v165, v165
	v_exp_f32_e32 v166, v166
	v_exp_f32_e32 v167, v167
	v_add_f32_e32 v160, 1.0, v160
	v_add_f32_e32 v161, 1.0, v161
	v_add_f32_e32 v162, 1.0, v162
	v_add_f32_e32 v163, 1.0, v163
	v_add_f32_e32 v164, 1.0, v164
	v_add_f32_e32 v165, 1.0, v165
	v_add_f32_e32 v166, 1.0, v166
	v_add_f32_e32 v167, 1.0, v167
	v_rcp_f32_e32 v160, v160
	v_rcp_f32_e32 v161, v161
	v_rcp_f32_e32 v162, v162
	v_rcp_f32_e32 v163, v163
	v_rcp_f32_e32 v164, v164
	v_rcp_f32_e32 v165, v165
	v_rcp_f32_e32 v166, v166
	v_rcp_f32_e32 v167, v167
	v_mul_f32_e32 v92, v92, v160
	v_mul_f32_e32 v93, v93, v161
	v_mul_f32_e32 v94, v94, v162
	v_mul_f32_e32 v95, v95, v163
	v_mul_f32_e32 v84, v84, v164
	v_mul_f32_e32 v85, v85, v165
	v_mul_f32_e32 v86, v86, v166
	v_mul_f32_e32 v87, v87, v167
	v_mul_f32_e32 v88, v92, v88
	v_mul_f32_e32 v89, v93, v89
	v_mul_f32_e32 v90, v94, v90
	v_mul_f32_e32 v91, v95, v91
	v_mul_f32_e32 v80, v84, v80
	v_mul_f32_e32 v81, v85, v81
	v_mul_f32_e32 v82, v86, v82
	v_mul_f32_e32 v83, v87, v83
	v_cvt_pk_bf16_f32 v92, v88, v89
	v_cvt_pk_bf16_f32 v93, v90, v91
	v_cvt_pk_bf16_f32 v94, v80, v81
	v_cvt_pk_bf16_f32 v95, v82, v83
	s_nop 1
	v_permlane16_swap_b32_e32 v92, v94
	v_permlane16_swap_b32_e32 v93, v95
	global_store_dwordx4 v168, v[92:95], s[100:101] sc1
	s_add_u32 s100, s100, 0x16000
	s_addc_u32 s101, s101, 0
	v_mul_f32_e32 v160, 0xbfb8aa3b, v76
	v_mul_f32_e32 v161, 0xbfb8aa3b, v77
	v_mul_f32_e32 v162, 0xbfb8aa3b, v78
	v_mul_f32_e32 v163, 0xbfb8aa3b, v79
	v_mul_f32_e32 v164, 0xbfb8aa3b, v68
	v_mul_f32_e32 v165, 0xbfb8aa3b, v69
	v_mul_f32_e32 v166, 0xbfb8aa3b, v70
	v_mul_f32_e32 v167, 0xbfb8aa3b, v71
	v_exp_f32_e32 v160, v160
	v_exp_f32_e32 v161, v161
	v_exp_f32_e32 v162, v162
	v_exp_f32_e32 v163, v163
	v_exp_f32_e32 v164, v164
	v_exp_f32_e32 v165, v165
	v_exp_f32_e32 v166, v166
	v_exp_f32_e32 v167, v167
	v_add_f32_e32 v160, 1.0, v160
	v_add_f32_e32 v161, 1.0, v161
	v_add_f32_e32 v162, 1.0, v162
	v_add_f32_e32 v163, 1.0, v163
	v_add_f32_e32 v164, 1.0, v164
	v_add_f32_e32 v165, 1.0, v165
	v_add_f32_e32 v166, 1.0, v166
	v_add_f32_e32 v167, 1.0, v167
	v_rcp_f32_e32 v160, v160
	v_rcp_f32_e32 v161, v161
	v_rcp_f32_e32 v162, v162
	v_rcp_f32_e32 v163, v163
	v_rcp_f32_e32 v164, v164
	v_rcp_f32_e32 v165, v165
	v_rcp_f32_e32 v166, v166
	v_rcp_f32_e32 v167, v167
	v_mul_f32_e32 v76, v76, v160
	v_mul_f32_e32 v77, v77, v161
	v_mul_f32_e32 v78, v78, v162
	v_mul_f32_e32 v79, v79, v163
	v_mul_f32_e32 v68, v68, v164
	v_mul_f32_e32 v69, v69, v165
	v_mul_f32_e32 v70, v70, v166
	v_mul_f32_e32 v71, v71, v167
	v_mul_f32_e32 v72, v76, v72
	v_mul_f32_e32 v73, v77, v73
	v_mul_f32_e32 v74, v78, v74
	v_mul_f32_e32 v75, v79, v75
	v_mul_f32_e32 v64, v68, v64
	v_mul_f32_e32 v65, v69, v65
	v_mul_f32_e32 v66, v70, v66
	v_mul_f32_e32 v67, v71, v67
	v_cvt_pk_bf16_f32 v76, v72, v73
	v_cvt_pk_bf16_f32 v77, v74, v75
	v_cvt_pk_bf16_f32 v78, v64, v65
	v_cvt_pk_bf16_f32 v79, v66, v67
	s_nop 1
	v_permlane16_swap_b32_e32 v76, v78
	v_permlane16_swap_b32_e32 v77, v79
	global_store_dwordx4 v168, v[76:79], s[100:101] sc1
	s_add_u32 s100, s100, 0x16000
	s_addc_u32 s101, s101, 0
	v_mul_f32_e32 v160, 0xbfb8aa3b, v60
	v_mul_f32_e32 v161, 0xbfb8aa3b, v61
	v_mul_f32_e32 v162, 0xbfb8aa3b, v62
	v_mul_f32_e32 v163, 0xbfb8aa3b, v63
	v_mul_f32_e32 v164, 0xbfb8aa3b, v52
	v_mul_f32_e32 v165, 0xbfb8aa3b, v53
	v_mul_f32_e32 v166, 0xbfb8aa3b, v54
	v_mul_f32_e32 v167, 0xbfb8aa3b, v55
	v_exp_f32_e32 v160, v160
	v_exp_f32_e32 v161, v161
	v_exp_f32_e32 v162, v162
	v_exp_f32_e32 v163, v163
	v_exp_f32_e32 v164, v164
	v_exp_f32_e32 v165, v165
	v_exp_f32_e32 v166, v166
	v_exp_f32_e32 v167, v167
	v_add_f32_e32 v160, 1.0, v160
	v_add_f32_e32 v161, 1.0, v161
	v_add_f32_e32 v162, 1.0, v162
	v_add_f32_e32 v163, 1.0, v163
	v_add_f32_e32 v164, 1.0, v164
	v_add_f32_e32 v165, 1.0, v165
	v_add_f32_e32 v166, 1.0, v166
	v_add_f32_e32 v167, 1.0, v167
	v_rcp_f32_e32 v160, v160
	v_rcp_f32_e32 v161, v161
	v_rcp_f32_e32 v162, v162
	v_rcp_f32_e32 v163, v163
	v_rcp_f32_e32 v164, v164
	v_rcp_f32_e32 v165, v165
	v_rcp_f32_e32 v166, v166
	v_rcp_f32_e32 v167, v167
	v_mul_f32_e32 v60, v60, v160
	v_mul_f32_e32 v61, v61, v161
	v_mul_f32_e32 v62, v62, v162
	v_mul_f32_e32 v63, v63, v163
	v_mul_f32_e32 v52, v52, v164
	v_mul_f32_e32 v53, v53, v165
	v_mul_f32_e32 v54, v54, v166
	v_mul_f32_e32 v55, v55, v167
	v_mul_f32_e32 v56, v60, v56
	v_mul_f32_e32 v57, v61, v57
	v_mul_f32_e32 v58, v62, v58
	v_mul_f32_e32 v59, v63, v59
	v_mul_f32_e32 v48, v52, v48
	v_mul_f32_e32 v49, v53, v49
	v_mul_f32_e32 v50, v54, v50
	v_mul_f32_e32 v51, v55, v51
	v_cvt_pk_bf16_f32 v60, v56, v57
	v_cvt_pk_bf16_f32 v61, v58, v59
	v_cvt_pk_bf16_f32 v62, v48, v49
	v_cvt_pk_bf16_f32 v63, v50, v51
	s_nop 1
	v_permlane16_swap_b32_e32 v60, v62
	v_permlane16_swap_b32_e32 v61, v63
	global_store_dwordx4 v168, v[60:63], s[100:101] sc1
	s_add_u32 s100, s100, 0x16000
	s_addc_u32 s101, s101, 0
	v_mul_f32_e32 v160, 0xbfb8aa3b, v36
	v_mul_f32_e32 v161, 0xbfb8aa3b, v37
	v_mul_f32_e32 v162, 0xbfb8aa3b, v38
	v_mul_f32_e32 v163, 0xbfb8aa3b, v39
	v_mul_f32_e32 v164, 0xbfb8aa3b, v44
	v_mul_f32_e32 v165, 0xbfb8aa3b, v45
	v_mul_f32_e32 v166, 0xbfb8aa3b, v46
	v_mul_f32_e32 v167, 0xbfb8aa3b, v47
	v_exp_f32_e32 v160, v160
	v_exp_f32_e32 v161, v161
	v_exp_f32_e32 v162, v162
	v_exp_f32_e32 v163, v163
	v_exp_f32_e32 v164, v164
	v_exp_f32_e32 v165, v165
	v_exp_f32_e32 v166, v166
	v_exp_f32_e32 v167, v167
	v_add_f32_e32 v160, 1.0, v160
	v_add_f32_e32 v161, 1.0, v161
	v_add_f32_e32 v162, 1.0, v162
	v_add_f32_e32 v163, 1.0, v163
	v_add_f32_e32 v164, 1.0, v164
	v_add_f32_e32 v165, 1.0, v165
	v_add_f32_e32 v166, 1.0, v166
	v_add_f32_e32 v167, 1.0, v167
	v_rcp_f32_e32 v160, v160
	v_rcp_f32_e32 v161, v161
	v_rcp_f32_e32 v162, v162
	v_rcp_f32_e32 v163, v163
	v_rcp_f32_e32 v164, v164
	v_rcp_f32_e32 v165, v165
	v_rcp_f32_e32 v166, v166
	v_rcp_f32_e32 v167, v167
	v_mul_f32_e32 v36, v36, v160
	v_mul_f32_e32 v37, v37, v161
	v_mul_f32_e32 v38, v38, v162
	v_mul_f32_e32 v39, v39, v163
	v_mul_f32_e32 v44, v44, v164
	v_mul_f32_e32 v45, v45, v165
	v_mul_f32_e32 v46, v46, v166
	v_mul_f32_e32 v47, v47, v167
	v_mul_f32_e32 v32, v36, v32
	v_mul_f32_e32 v33, v37, v33
	v_mul_f32_e32 v34, v38, v34
	v_mul_f32_e32 v35, v39, v35
	v_mul_f32_e32 v40, v44, v40
	v_mul_f32_e32 v41, v45, v41
	v_mul_f32_e32 v42, v46, v42
	v_mul_f32_e32 v43, v47, v43
	v_cvt_pk_bf16_f32 v36, v32, v33
	v_cvt_pk_bf16_f32 v37, v34, v35
	v_cvt_pk_bf16_f32 v38, v40, v41
	v_cvt_pk_bf16_f32 v39, v42, v43
	s_nop 1
	v_permlane16_swap_b32_e32 v36, v38
	v_permlane16_swap_b32_e32 v37, v39
	global_store_dwordx4 v168, v[36:39], s[100:101] sc1
	s_and_b64 vcc, exec, s[16:17]
	s_mov_b32 s24, s20
	s_mov_b32 s22, s18
	s_mov_b64 s[26:27], s[12:13]
	s_mov_b64 s[4:5], s[10:11]
	s_cbranch_vccz .LBB0_1143

.LBB0_1208:
	ds_read_b128 v[160:163], v200
	ds_read_b128 v[164:167], v201
	ds_read_b128 v[180:183], v201 offset:64
	ds_read_b128 v[168:171], v200 offset:64
	ds_read_b128 v[172:175], v201 offset:2304
	ds_read_b128 v[192:195], v201 offset:2368
	ds_read_b128 v[176:179], v201 offset:4608
	ds_read_b128 v[210:213], v201 offset:4672
	ds_read_b128 v[184:187], v201 offset:6912
	ds_read_b128 v[214:217], v201 offset:6976
	s_waitcnt lgkmcnt(8)
	v_mfma_f32_16x16x32_bf16 v[156:159], v[164:167], v[160:163], v[156:159]
	s_add_i32 s80, s79, 2
	s_add_u32 s81, s52, 0xffffff80
	s_addc_u32 s83, s53, -1
	s_waitcnt lgkmcnt(5)
	v_mfma_f32_16x16x32_bf16 v[152:155], v[172:175], v[160:163], v[152:155]
	s_add_u32 s84, s54, 0xffffff80
	s_addc_u32 s85, s55, -1
	s_cmp_lt_u32 s79, 20
	s_waitcnt lgkmcnt(3)
	v_mfma_f32_16x16x32_bf16 v[148:151], v[176:179], v[160:163], v[148:151]
	s_cselect_b32 s82, s81, s44
	s_cselect_b32 s83, s83, s45
	s_cselect_b32 s84, s84, s48
	s_waitcnt lgkmcnt(1)
	v_mfma_f32_16x16x32_bf16 v[144:147], v[184:187], v[160:163], v[144:147]
	ds_read_b128 v[160:163], v200 offset:2304
	ds_read_b128 v[188:191], v200 offset:2368
	s_cselect_b32 s85, s85, s49
	s_cmp_lt_u32 s79, 19
	s_waitcnt lgkmcnt(1)
	v_mfma_f32_16x16x32_bf16 v[140:143], v[164:167], v[160:163], v[140:143]
	v_mfma_f32_16x16x32_bf16 v[136:139], v[172:175], v[160:163], v[136:139]
	v_mfma_f32_16x16x32_bf16 v[132:135], v[176:179], v[160:163], v[132:135]
	v_mfma_f32_16x16x32_bf16 v[128:131], v[184:187], v[160:163], v[128:131]
	ds_read_b128 v[160:163], v200 offset:4608
	ds_read_b128 v[218:221], v200 offset:4672
	s_waitcnt lgkmcnt(1)
	v_mfma_f32_16x16x32_bf16 v[124:127], v[164:167], v[160:163], v[124:127]
	v_mfma_f32_16x16x32_bf16 v[120:123], v[172:175], v[160:163], v[120:123]
	v_mfma_f32_16x16x32_bf16 v[116:119], v[176:179], v[160:163], v[116:119]
	v_mfma_f32_16x16x32_bf16 v[112:115], v[184:187], v[160:163], v[112:115]
	ds_read_b128 v[160:163], v200 offset:6912
	ds_read_b128 v[222:225], v200 offset:6976
	s_waitcnt lgkmcnt(1)
	v_mfma_f32_16x16x32_bf16 v[108:111], v[164:167], v[160:163], v[108:111]
	v_mfma_f32_16x16x32_bf16 v[104:107], v[172:175], v[160:163], v[104:107]
	v_mfma_f32_16x16x32_bf16 v[100:103], v[176:179], v[160:163], v[100:103]
	v_mfma_f32_16x16x32_bf16 v[96:99], v[184:187], v[160:163], v[96:99]
	ds_read_b128 v[160:163], v200 offset:9216
	ds_read_b128 v[226:229], v200 offset:9280
	s_waitcnt lgkmcnt(1)
	v_mfma_f32_16x16x32_bf16 v[92:95], v[164:167], v[160:163], v[92:95]
	v_mfma_f32_16x16x32_bf16 v[88:91], v[172:175], v[160:163], v[88:91]
	v_mfma_f32_16x16x32_bf16 v[80:83], v[176:179], v[160:163], v[80:83]
	v_mfma_f32_16x16x32_bf16 v[84:87], v[184:187], v[160:163], v[84:87]
	ds_read_b128 v[160:163], v200 offset:11520
	ds_read_b128 v[230:233], v200 offset:11584
	s_waitcnt lgkmcnt(1)
	v_mfma_f32_16x16x32_bf16 v[76:79], v[164:167], v[160:163], v[76:79]
	v_mfma_f32_16x16x32_bf16 v[72:75], v[172:175], v[160:163], v[72:75]
	v_mfma_f32_16x16x32_bf16 v[68:71], v[176:179], v[160:163], v[68:71]
	v_mfma_f32_16x16x32_bf16 v[64:67], v[184:187], v[160:163], v[64:67]
	ds_read_b128 v[160:163], v200 offset:13824
	ds_read_b128 v[234:237], v200 offset:13888
	s_waitcnt lgkmcnt(1)
	v_mfma_f32_16x16x32_bf16 v[60:63], v[164:167], v[160:163], v[60:63]
	v_mfma_f32_16x16x32_bf16 v[56:59], v[172:175], v[160:163], v[56:59]
	v_mfma_f32_16x16x32_bf16 v[52:55], v[176:179], v[160:163], v[52:55]
	v_mfma_f32_16x16x32_bf16 v[48:51], v[184:187], v[160:163], v[48:51]
	ds_read_b128 v[160:163], v200 offset:16128
	ds_read_b128 v[238:241], v200 offset:16192
	s_setprio 0
	s_waitcnt vmcnt(6)
	ds_write_b128 v202, v[4:7] offset:36864
	s_waitcnt vmcnt(5)
	ds_write_b128 v202, v[8:11] offset:46080
	s_waitcnt vmcnt(4)
	ds_write_b128 v202, v[12:15] offset:55296
	s_waitcnt vmcnt(3)
	ds_write_b128 v202, v[16:19] offset:64512
	v_mfma_f32_16x16x32_bf16 v[16:19], v[210:213], v[226:229], v[80:83]
	s_waitcnt vmcnt(3)
	ds_write_b128 v208, v[0:3]
	s_waitcnt vmcnt(2)
	ds_write_b128 v208, v[20:23] offset:9216
	s_waitcnt vmcnt(1)
	ds_write_b128 v208, v[24:27] offset:18432
	v_lshl_add_u64 v[80:81], s[82:83], 0, v[196:197]
	s_waitcnt vmcnt(0)
	ds_write_b128 v208, v[28:31] offset:27648
	v_mfma_f32_16x16x32_bf16 v[24:27], v[180:183], v[230:233], v[76:79]
	v_lshl_add_u64 v[82:83], s[84:85], 0, v[196:197]
	s_cselect_b32 s82, s52, s75
	s_cselect_b32 s83, s53, s76
	v_add_co_u32_e32 v76, vcc, s57, v80
	v_mfma_f32_16x16x32_bf16 v[28:31], v[192:195], v[230:233], v[72:75]
	s_nop 0
	v_addc_co_u32_e32 v77, vcc, 0, v81, vcc
	s_cselect_b32 s84, s54, s77
	v_add_co_u32_e32 v72, vcc, s58, v80
	s_waitcnt lgkmcnt(9)
	v_mfma_f32_16x16x32_bf16 v[40:43], v[164:167], v[160:163], v[40:43]
	v_addc_co_u32_e32 v73, vcc, 0, v81, vcc
	v_add_co_u32_e32 v74, vcc, s59, v80
	v_mfma_f32_16x16x32_bf16 v[36:39], v[172:175], v[160:163], v[36:39]
	s_nop 0
	v_addc_co_u32_e32 v75, vcc, 0, v81, vcc
	v_add_co_u32_e32 v78, vcc, s57, v82
	v_mfma_f32_16x16x32_bf16 v[32:35], v[176:179], v[160:163], v[32:35]
	s_nop 0
	v_addc_co_u32_e32 v79, vcc, 0, v83, vcc
	global_load_dwordx4 v[164:167], v[82:83], off
	v_mfma_f32_16x16x32_bf16 v[44:47], v[184:187], v[160:163], v[44:47]
	global_load_dwordx4 v[160:163], v[80:81], off
	v_add_co_u32_e32 v80, vcc, s58, v82
	v_mfma_f32_16x16x32_bf16 v[156:159], v[180:183], v[168:171], v[156:159]
	s_nop 0
	v_addc_co_u32_e32 v81, vcc, 0, v83, vcc
	v_add_co_u32_e32 v82, vcc, s59, v82
	v_mfma_f32_16x16x32_bf16 v[152:155], v[192:195], v[168:171], v[152:155]
	s_nop 0
	v_addc_co_u32_e32 v83, vcc, 0, v83, vcc
	s_cselect_b32 s85, s55, s78
	v_mfma_f32_16x16x32_bf16 v[148:151], v[210:213], v[168:171], v[148:151]
	s_add_u32 s54, s54, 0x100
	s_addc_u32 s55, s55, 0
	s_add_u32 s52, s52, 0x100
	v_mfma_f32_16x16x32_bf16 v[144:147], v[214:217], v[168:171], v[144:147]
	global_load_dwordx4 v[168:171], v[76:77], off
	global_load_dwordx4 v[172:175], v[72:73], off
	global_load_dwordx4 v[176:179], v[74:75], off
	s_addc_u32 s53, s53, 0
	s_cmp_gt_u32 s79, 19
	v_mfma_f32_16x16x32_bf16 v[140:143], v[180:183], v[188:191], v[140:143]
	s_mov_b32 s79, s80
	v_mfma_f32_16x16x32_bf16 v[136:139], v[192:195], v[188:191], v[136:139]
	v_mfma_f32_16x16x32_bf16 v[132:135], v[210:213], v[188:191], v[132:135]
	v_mfma_f32_16x16x32_bf16 v[128:131], v[214:217], v[188:191], v[128:131]
	v_mfma_f32_16x16x32_bf16 v[124:127], v[180:183], v[218:221], v[124:127]
	v_mfma_f32_16x16x32_bf16 v[108:111], v[180:183], v[222:225], v[108:111]
	v_mfma_f32_16x16x32_bf16 v[0:3], v[180:183], v[226:229], v[92:95]
	v_mfma_f32_16x16x32_bf16 v[60:63], v[180:183], v[234:237], v[60:63]
	s_waitcnt lgkmcnt(8)
	v_mfma_f32_16x16x32_bf16 v[40:43], v[180:183], v[238:241], v[40:43]
	global_load_dwordx4 v[180:183], v[78:79], off
	global_load_dwordx4 v[184:187], v[80:81], off
	global_load_dwordx4 v[188:191], v[82:83], off
	s_waitcnt lgkmcnt(0)
	s_barrier
	s_setprio 1
	ds_read_b128 v[72:75], v200 offset:36864
	v_mfma_f32_16x16x32_bf16 v[116:119], v[210:213], v[218:221], v[116:119]
	v_mfma_f32_16x16x32_bf16 v[112:115], v[214:217], v[218:221], v[112:115]
	v_mfma_f32_16x16x32_bf16 v[4:7], v[210:213], v[222:225], v[100:103]
	v_mfma_f32_16x16x32_bf16 v[8:11], v[214:217], v[222:225], v[96:99]
	v_mfma_f32_16x16x32_bf16 v[20:23], v[214:217], v[226:229], v[84:87]
	v_mfma_f32_16x16x32_bf16 v[68:71], v[210:213], v[230:233], v[68:71]
	v_mfma_f32_16x16x32_bf16 v[64:67], v[214:217], v[230:233], v[64:67]
	v_mfma_f32_16x16x32_bf16 v[52:55], v[210:213], v[234:237], v[52:55]
	v_mfma_f32_16x16x32_bf16 v[48:51], v[214:217], v[234:237], v[48:51]
	v_mfma_f32_16x16x32_bf16 v[32:35], v[210:213], v[238:241], v[32:35]
	ds_read_b128 v[80:83], v209
	ds_read_b128 v[210:213], v209 offset:64
	ds_read_b128 v[84:87], v200 offset:36928
	v_mfma_f32_16x16x32_bf16 v[76:79], v[214:217], v[238:241], v[44:47]
	ds_read_b128 v[92:95], v209 offset:2304
	ds_read_b128 v[214:217], v209 offset:2368
	v_mfma_f32_16x16x32_bf16 v[120:123], v[192:195], v[218:221], v[120:123]
	ds_read_b128 v[100:103], v209 offset:4608
	ds_read_b128 v[218:221], v209 offset:4672
	s_waitcnt lgkmcnt(3)
	v_mfma_f32_16x16x32_bf16 v[96:99], v[92:95], v[72:75], v[152:155]
	s_nop 2
	ds_read_b128 v[152:155], v209 offset:6912
	ds_read_b128 v[44:47], v209 offset:6976
	v_mfma_f32_16x16x32_bf16 v[104:107], v[192:195], v[222:225], v[104:107]
	v_mfma_f32_16x16x32_bf16 v[12:15], v[192:195], v[226:229], v[88:91]
	v_mfma_f32_16x16x32_bf16 v[88:91], v[80:83], v[72:75], v[156:159]
	s_waitcnt lgkmcnt(3)
	v_mfma_f32_16x16x32_bf16 v[148:151], v[100:103], v[72:75], v[148:151]
	s_waitcnt lgkmcnt(1)
	v_mfma_f32_16x16x32_bf16 v[72:75], v[152:155], v[72:75], v[144:147]
	s_nop 2
	ds_read_b128 v[144:147], v200 offset:39168
	ds_read_b128 v[222:225], v200 offset:39232
	s_waitcnt lgkmcnt(1)
	v_mfma_f32_16x16x32_bf16 v[140:143], v[80:83], v[144:147], v[140:143]
	v_mfma_f32_16x16x32_bf16 v[136:139], v[92:95], v[144:147], v[136:139]
	v_mfma_f32_16x16x32_bf16 v[132:135], v[100:103], v[144:147], v[132:135]
	v_mfma_f32_16x16x32_bf16 v[128:131], v[152:155], v[144:147], v[128:131]
	ds_read_b128 v[144:147], v200 offset:41472
	ds_read_b128 v[226:229], v200 offset:41536
	s_waitcnt lgkmcnt(1)
	v_mfma_f32_16x16x32_bf16 v[124:127], v[80:83], v[144:147], v[124:127]
	v_mfma_f32_16x16x32_bf16 v[120:123], v[92:95], v[144:147], v[120:123]
	v_mfma_f32_16x16x32_bf16 v[116:119], v[100:103], v[144:147], v[116:119]
	v_mfma_f32_16x16x32_bf16 v[112:115], v[152:155], v[144:147], v[112:115]
	ds_read_b128 v[144:147], v200 offset:43776
	ds_read_b128 v[230:233], v200 offset:43840
	v_mfma_f32_16x16x32_bf16 v[56:59], v[192:195], v[234:237], v[56:59]
	s_waitcnt lgkmcnt(1)
	v_mfma_f32_16x16x32_bf16 v[108:111], v[80:83], v[144:147], v[108:111]
	v_mfma_f32_16x16x32_bf16 v[104:107], v[92:95], v[144:147], v[104:107]
	v_mfma_f32_16x16x32_bf16 v[4:7], v[100:103], v[144:147], v[4:7]
	v_mfma_f32_16x16x32_bf16 v[8:11], v[152:155], v[144:147], v[8:11]
	ds_read_b128 v[144:147], v200 offset:46080
	ds_read_b128 v[234:237], v200 offset:46144
	v_mfma_f32_16x16x32_bf16 v[36:39], v[192:195], v[238:241], v[36:39]
	s_waitcnt lgkmcnt(1)
	v_mfma_f32_16x16x32_bf16 v[0:3], v[80:83], v[144:147], v[0:3]
	v_mfma_f32_16x16x32_bf16 v[12:15], v[92:95], v[144:147], v[12:15]
	v_mfma_f32_16x16x32_bf16 v[16:19], v[100:103], v[144:147], v[16:19]
	v_mfma_f32_16x16x32_bf16 v[20:23], v[152:155], v[144:147], v[20:23]
	ds_read_b128 v[144:147], v200 offset:48384
	ds_read_b128 v[238:241], v200 offset:48448
	s_waitcnt lgkmcnt(1)
	v_mfma_f32_16x16x32_bf16 v[24:27], v[80:83], v[144:147], v[24:27]
	v_mfma_f32_16x16x32_bf16 v[28:31], v[92:95], v[144:147], v[28:31]
	v_mfma_f32_16x16x32_bf16 v[68:71], v[100:103], v[144:147], v[68:71]
	v_mfma_f32_16x16x32_bf16 v[64:67], v[152:155], v[144:147], v[64:67]
	ds_read_b128 v[144:147], v200 offset:50688
	ds_read_b128 v[242:245], v200 offset:50752
	s_waitcnt lgkmcnt(1)
	v_mfma_f32_16x16x32_bf16 v[60:63], v[80:83], v[144:147], v[60:63]
	v_mfma_f32_16x16x32_bf16 v[56:59], v[92:95], v[144:147], v[56:59]
	v_mfma_f32_16x16x32_bf16 v[52:55], v[100:103], v[144:147], v[52:55]
	v_mfma_f32_16x16x32_bf16 v[48:51], v[152:155], v[144:147], v[48:51]
	ds_read_b128 v[144:147], v200 offset:52992
	ds_read_b128 v[192:195], v200 offset:53056
	s_waitcnt lgkmcnt(1)
	v_mfma_f32_16x16x32_bf16 v[32:35], v[100:103], v[144:147], v[32:35]
	v_mfma_f32_16x16x32_bf16 v[100:103], v[218:221], v[230:233], v[4:7]
	s_nop 2
	v_lshl_add_u64 v[4:5], s[82:83], 0, v[196:197]
	v_mfma_f32_16x16x32_bf16 v[246:249], v[152:155], v[144:147], v[76:79]
	v_lshl_add_u64 v[6:7], s[84:85], 0, v[196:197]
	v_mfma_f32_16x16x32_bf16 v[152:155], v[214:217], v[84:87], v[96:99]
	v_mfma_f32_16x16x32_bf16 v[96:99], v[44:47], v[230:233], v[8:11]
	s_nop 2
	v_add_co_u32_e32 v8, vcc, s57, v4
	v_mfma_f32_16x16x32_bf16 v[156:159], v[210:213], v[84:87], v[88:91]
	s_nop 0
	v_addc_co_u32_e32 v9, vcc, 0, v5, vcc
	v_mfma_f32_16x16x32_bf16 v[88:91], v[214:217], v[234:237], v[12:15]
	s_nop 2
	v_add_co_u32_e32 v12, vcc, s58, v4
	v_mfma_f32_16x16x32_bf16 v[40:43], v[80:83], v[144:147], v[40:43]
	s_nop 0
	v_addc_co_u32_e32 v13, vcc, 0, v5, vcc
	v_mfma_f32_16x16x32_bf16 v[80:83], v[218:221], v[234:237], v[16:19]
	s_nop 2
	v_add_co_u32_e32 v16, vcc, s59, v4
	v_mfma_f32_16x16x32_bf16 v[36:39], v[92:95], v[144:147], v[36:39]
	s_nop 0
	v_addc_co_u32_e32 v17, vcc, 0, v5, vcc
	v_mfma_f32_16x16x32_bf16 v[148:151], v[218:221], v[84:87], v[148:151]
	v_mfma_f32_16x16x32_bf16 v[144:147], v[44:47], v[84:87], v[72:75]
	v_mfma_f32_16x16x32_bf16 v[84:87], v[44:47], v[234:237], v[20:23]
	s_nop 2
	v_add_co_u32_e32 v20, vcc, s57, v6
	v_mfma_f32_16x16x32_bf16 v[76:79], v[210:213], v[238:241], v[24:27]
	s_nop 0
	v_addc_co_u32_e32 v21, vcc, 0, v7, vcc
	s_nop 0
	v_add_co_u32_e32 v24, vcc, s58, v6
	v_mfma_f32_16x16x32_bf16 v[72:75], v[214:217], v[238:241], v[28:31]
	s_nop 0
	v_addc_co_u32_e32 v25, vcc, 0, v7, vcc
	s_nop 0
	v_add_co_u32_e32 v28, vcc, s59, v6
	v_mfma_f32_16x16x32_bf16 v[92:95], v[210:213], v[234:237], v[0:3]
	s_nop 0
	v_addc_co_u32_e32 v29, vcc, 0, v7, vcc
	s_nop 0
	global_load_dwordx4 v[0:3], v[6:7], off
	s_nop 0
	global_load_dwordx4 v[4:7], v[4:5], off
	s_nop 0
	global_load_dwordx4 v[8:11], v[8:9], off
	s_nop 0
	global_load_dwordx4 v[12:15], v[12:13], off
	s_nop 0
	global_load_dwordx4 v[16:19], v[16:17], off
	s_nop 0
	global_load_dwordx4 v[20:23], v[20:21], off
	s_nop 0
	global_load_dwordx4 v[24:27], v[24:25], off
	v_mfma_f32_16x16x32_bf16 v[140:143], v[210:213], v[222:225], v[140:143]
	global_load_dwordx4 v[28:31], v[28:29], off
	s_setprio 0
	s_waitcnt vmcnt(14)
	ds_write_b128 v202, v[160:163]
	ds_write_b128 v206, v[164:167]
	s_waitcnt vmcnt(13)
	ds_write_b128 v202, v[168:171] offset:9216
	s_waitcnt vmcnt(12)
	ds_write_b128 v202, v[172:175] offset:18432
	s_waitcnt vmcnt(11)
	ds_write_b128 v202, v[176:179] offset:27648
	s_waitcnt vmcnt(10)
	ds_write_b128 v206, v[180:183] offset:9216
	s_waitcnt vmcnt(9)
	ds_write_b128 v206, v[184:187] offset:18432
	s_waitcnt vmcnt(8)
	ds_write_b128 v206, v[188:191] offset:27648
	s_waitcnt lgkmcnt(0)
	v_mfma_f32_16x16x32_bf16 v[136:139], v[214:217], v[222:225], v[136:139]
	s_barrier
	s_setprio 1
	v_mfma_f32_16x16x32_bf16 v[132:135], v[218:221], v[222:225], v[132:135]
	v_mfma_f32_16x16x32_bf16 v[128:131], v[44:47], v[222:225], v[128:131]
	v_mfma_f32_16x16x32_bf16 v[124:127], v[210:213], v[226:229], v[124:127]
	v_mfma_f32_16x16x32_bf16 v[120:123], v[214:217], v[226:229], v[120:123]
	v_mfma_f32_16x16x32_bf16 v[116:119], v[218:221], v[226:229], v[116:119]
	v_mfma_f32_16x16x32_bf16 v[112:115], v[44:47], v[226:229], v[112:115]
	v_mfma_f32_16x16x32_bf16 v[108:111], v[210:213], v[230:233], v[108:111]
	v_mfma_f32_16x16x32_bf16 v[104:107], v[214:217], v[230:233], v[104:107]
	v_mfma_f32_16x16x32_bf16 v[68:71], v[218:221], v[238:241], v[68:71]
	v_mfma_f32_16x16x32_bf16 v[64:67], v[44:47], v[238:241], v[64:67]
	v_mfma_f32_16x16x32_bf16 v[60:63], v[210:213], v[242:245], v[60:63]
	v_mfma_f32_16x16x32_bf16 v[56:59], v[214:217], v[242:245], v[56:59]
	v_mfma_f32_16x16x32_bf16 v[52:55], v[218:221], v[242:245], v[52:55]
	v_mfma_f32_16x16x32_bf16 v[48:51], v[44:47], v[242:245], v[48:51]
	v_mfma_f32_16x16x32_bf16 v[40:43], v[210:213], v[192:195], v[40:43]
	v_mfma_f32_16x16x32_bf16 v[36:39], v[214:217], v[192:195], v[36:39]
	v_mfma_f32_16x16x32_bf16 v[32:35], v[218:221], v[192:195], v[32:35]
	v_mfma_f32_16x16x32_bf16 v[44:47], v[44:47], v[192:195], v[246:249]
	s_cbranch_scc0 .LBB0_1208
	s_cmp_eq_u32 s72, 0
	s_mov_b32 s99, 0x6a44000
	s_cselect_b32 s99, s99, 0x7a44000
	s_lshl_b32 s98, s74, 11
	s_lshl_b32 s100, s73, 1
	s_add_u32 s98, s98, s100
	s_add_u32 s98, s98, s99
	s_add_u32 s100, s34, s98
	s_addc_u32 s101, s35, 0
	v_and_b32_e32 v160, 15, v207
	v_and_b32_e32 v161, 0x80, v203
	v_add_u32_e32 v160, v160, v161
	v_lshlrev_b32_e32 v160, 11, v160
	v_and_b32_e32 v161, 0xc0, v207
	v_lshl_add_u32 v160, v161, 1, v160
	v_and_b32_e32 v161, 4, v203
	v_lshl_add_u32 v160, v161, 3, v160
	v_and_b32_e32 v161, 8, v203
	v_lshl_add_u32 v160, v161, 1, v160
	v_cvt_pk_bf16_f32 v156, v156, v157
	v_cvt_pk_bf16_f32 v157, v158, v159
	v_cvt_pk_bf16_f32 v158, v152, v153
	v_cvt_pk_bf16_f32 v159, v154, v155
	v_cvt_pk_bf16_f32 v148, v148, v149
	v_cvt_pk_bf16_f32 v149, v150, v151
	v_cvt_pk_bf16_f32 v150, v144, v145
	v_cvt_pk_bf16_f32 v151, v146, v147
	v_permlane16_swap_b32_e32 v156, v158
	v_permlane16_swap_b32_e32 v157, v159
	v_permlane16_swap_b32_e32 v148, v150
	v_permlane16_swap_b32_e32 v149, v151
	global_store_dwordx4 v160, v[156:159], s[100:101] sc1
	global_store_dwordx4 v160, v[148:151], s[100:101] offset:64 sc1
	s_add_u32 s100, s100, 0x8000
	s_addc_u32 s101, s101, 0
	v_cvt_pk_bf16_f32 v140, v140, v141
	v_cvt_pk_bf16_f32 v141, v142, v143
	v_cvt_pk_bf16_f32 v142, v136, v137
	v_cvt_pk_bf16_f32 v143, v138, v139
	v_cvt_pk_bf16_f32 v132, v132, v133
	v_cvt_pk_bf16_f32 v133, v134, v135
	v_cvt_pk_bf16_f32 v134, v128, v129
	v_cvt_pk_bf16_f32 v135, v130, v131
	v_permlane16_swap_b32_e32 v140, v142
	v_permlane16_swap_b32_e32 v141, v143
	v_permlane16_swap_b32_e32 v132, v134
	v_permlane16_swap_b32_e32 v133, v135
	global_store_dwordx4 v160, v[140:143], s[100:101] sc1
	global_store_dwordx4 v160, v[132:135], s[100:101] offset:64 sc1
	s_add_u32 s100, s100, 0x8000
	s_addc_u32 s101, s101, 0
	v_cvt_pk_bf16_f32 v124, v124, v125
	v_cvt_pk_bf16_f32 v125, v126, v127
	v_cvt_pk_bf16_f32 v126, v120, v121
	v_cvt_pk_bf16_f32 v127, v122, v123
	v_cvt_pk_bf16_f32 v116, v116, v117
	v_cvt_pk_bf16_f32 v117, v118, v119
	v_cvt_pk_bf16_f32 v118, v112, v113
	v_cvt_pk_bf16_f32 v119, v114, v115
	v_permlane16_swap_b32_e32 v124, v126
	v_permlane16_swap_b32_e32 v125, v127
	v_permlane16_swap_b32_e32 v116, v118
	v_permlane16_swap_b32_e32 v117, v119
	global_store_dwordx4 v160, v[124:127], s[100:101] sc1
	global_store_dwordx4 v160, v[116:119], s[100:101] offset:64 sc1
	s_add_u32 s100, s100, 0x8000
	s_addc_u32 s101, s101, 0
	v_cvt_pk_bf16_f32 v108, v108, v109
	v_cvt_pk_bf16_f32 v109, v110, v111
	v_cvt_pk_bf16_f32 v110, v104, v105
	v_cvt_pk_bf16_f32 v111, v106, v107
	v_cvt_pk_bf16_f32 v100, v100, v101
	v_cvt_pk_bf16_f32 v101, v102, v103
	v_cvt_pk_bf16_f32 v102, v96, v97
	v_cvt_pk_bf16_f32 v103, v98, v99
	v_permlane16_swap_b32_e32 v108, v110
	v_permlane16_swap_b32_e32 v109, v111
	v_permlane16_swap_b32_e32 v100, v102
	v_permlane16_swap_b32_e32 v101, v103
	global_store_dwordx4 v160, v[108:111], s[100:101] sc1
	global_store_dwordx4 v160, v[100:103], s[100:101] offset:64 sc1
	s_add_u32 s100, s100, 0x8000
	s_addc_u32 s101, s101, 0
	v_cvt_pk_bf16_f32 v92, v92, v93
	v_cvt_pk_bf16_f32 v93, v94, v95
	v_cvt_pk_bf16_f32 v94, v88, v89
	v_cvt_pk_bf16_f32 v95, v90, v91
	v_cvt_pk_bf16_f32 v80, v80, v81
	v_cvt_pk_bf16_f32 v81, v82, v83
	v_cvt_pk_bf16_f32 v82, v84, v85
	v_cvt_pk_bf16_f32 v83, v86, v87
	v_permlane16_swap_b32_e32 v92, v94
	v_permlane16_swap_b32_e32 v93, v95
	v_permlane16_swap_b32_e32 v80, v82
	v_permlane16_swap_b32_e32 v81, v83
	global_store_dwordx4 v160, v[92:95], s[100:101] sc1
	global_store_dwordx4 v160, v[80:83], s[100:101] offset:64 sc1
	s_add_u32 s100, s100, 0x8000
	s_addc_u32 s101, s101, 0
	v_cvt_pk_bf16_f32 v76, v76, v77
	v_cvt_pk_bf16_f32 v77, v78, v79
	v_cvt_pk_bf16_f32 v78, v72, v73
	v_cvt_pk_bf16_f32 v79, v74, v75
	v_cvt_pk_bf16_f32 v68, v68, v69
	v_cvt_pk_bf16_f32 v69, v70, v71
	v_cvt_pk_bf16_f32 v70, v64, v65
	v_cvt_pk_bf16_f32 v71, v66, v67
	v_permlane16_swap_b32_e32 v76, v78
	v_permlane16_swap_b32_e32 v77, v79
	v_permlane16_swap_b32_e32 v68, v70
	v_permlane16_swap_b32_e32 v69, v71
	global_store_dwordx4 v160, v[76:79], s[100:101] sc1
	global_store_dwordx4 v160, v[68:71], s[100:101] offset:64 sc1
	s_add_u32 s100, s100, 0x8000
	s_addc_u32 s101, s101, 0
	v_cvt_pk_bf16_f32 v60, v60, v61
	v_cvt_pk_bf16_f32 v61, v62, v63
	v_cvt_pk_bf16_f32 v62, v56, v57
	v_cvt_pk_bf16_f32 v63, v58, v59
	v_cvt_pk_bf16_f32 v52, v52, v53
	v_cvt_pk_bf16_f32 v53, v54, v55
	v_cvt_pk_bf16_f32 v54, v48, v49
	v_cvt_pk_bf16_f32 v55, v50, v51
	v_permlane16_swap_b32_e32 v60, v62
	v_permlane16_swap_b32_e32 v61, v63
	v_permlane16_swap_b32_e32 v52, v54
	v_permlane16_swap_b32_e32 v53, v55
	global_store_dwordx4 v160, v[60:63], s[100:101] sc1
	global_store_dwordx4 v160, v[52:55], s[100:101] offset:64 sc1
	s_add_u32 s100, s100, 0x8000
	s_addc_u32 s101, s101, 0
	v_cvt_pk_bf16_f32 v40, v40, v41
	v_cvt_pk_bf16_f32 v41, v42, v43
	v_cvt_pk_bf16_f32 v42, v36, v37
	v_cvt_pk_bf16_f32 v43, v38, v39
	v_cvt_pk_bf16_f32 v32, v32, v33
	v_cvt_pk_bf16_f32 v33, v34, v35
	v_cvt_pk_bf16_f32 v34, v44, v45
	v_cvt_pk_bf16_f32 v35, v46, v47
	v_permlane16_swap_b32_e32 v40, v42
	v_permlane16_swap_b32_e32 v41, v43
	v_permlane16_swap_b32_e32 v32, v34
	v_permlane16_swap_b32_e32 v33, v35
	global_store_dwordx4 v160, v[40:43], s[100:101] sc1
	global_store_dwordx4 v160, v[32:35], s[100:101] offset:64 sc1
	s_and_b64 vcc, exec, s[50:51]
	s_mov_b32 s72, s71
	s_mov_b32 s73, s70
	s_mov_b32 s74, s69
	s_mov_b64 s[54:55], s[48:49]
	s_mov_b64 s[52:53], s[44:45]
	s_cbranch_vccz .LBB0_1205
	s_load_dwordx16 s[36:51], s[0:1], 0xc0

.LBB0_1511:
	ds_read_b128 v[160:163], v200
	ds_read_b128 v[164:167], v201
	ds_read_b128 v[180:183], v201 offset:64
	ds_read_b128 v[168:171], v200 offset:64
	ds_read_b128 v[172:175], v201 offset:2304
	ds_read_b128 v[192:195], v201 offset:2368
	ds_read_b128 v[176:179], v201 offset:4608
	ds_read_b128 v[210:213], v201 offset:4672
	ds_read_b128 v[184:187], v201 offset:6912
	ds_read_b128 v[214:217], v201 offset:6976
	s_waitcnt lgkmcnt(8)
	v_mfma_f32_16x16x32_bf16 v[156:159], v[164:167], v[160:163], v[156:159]
	s_add_i32 s86, s85, 2
	s_add_u32 s87, s56, 0xffffff80
	s_addc_u32 s93, s57, -1
	s_waitcnt lgkmcnt(5)
	v_mfma_f32_16x16x32_bf16 v[152:155], v[172:175], v[160:163], v[152:155]
	s_add_u32 s94, s58, 0xffffff80
	s_addc_u32 s95, s59, -1
	s_cmp_lt_u32 s85, 20
	s_waitcnt lgkmcnt(3)
	v_mfma_f32_16x16x32_bf16 v[148:151], v[176:179], v[160:163], v[148:151]
	s_cselect_b32 s92, s87, s50
	s_cselect_b32 s93, s93, s51
	s_cselect_b32 s94, s94, s52
	s_waitcnt lgkmcnt(1)
	v_mfma_f32_16x16x32_bf16 v[144:147], v[184:187], v[160:163], v[144:147]
	ds_read_b128 v[160:163], v200 offset:2304
	ds_read_b128 v[188:191], v200 offset:2368
	s_cselect_b32 s95, s95, s53
	s_cmp_lt_u32 s85, 19
	s_waitcnt lgkmcnt(1)
	v_mfma_f32_16x16x32_bf16 v[140:143], v[164:167], v[160:163], v[140:143]
	v_mfma_f32_16x16x32_bf16 v[136:139], v[172:175], v[160:163], v[136:139]
	v_mfma_f32_16x16x32_bf16 v[132:135], v[176:179], v[160:163], v[132:135]
	v_mfma_f32_16x16x32_bf16 v[128:131], v[184:187], v[160:163], v[128:131]
	ds_read_b128 v[160:163], v200 offset:4608
	ds_read_b128 v[218:221], v200 offset:4672
	s_waitcnt lgkmcnt(1)
	v_mfma_f32_16x16x32_bf16 v[124:127], v[164:167], v[160:163], v[124:127]
	v_mfma_f32_16x16x32_bf16 v[120:123], v[172:175], v[160:163], v[120:123]
	v_mfma_f32_16x16x32_bf16 v[116:119], v[176:179], v[160:163], v[116:119]
	v_mfma_f32_16x16x32_bf16 v[112:115], v[184:187], v[160:163], v[112:115]
	ds_read_b128 v[160:163], v200 offset:6912
	ds_read_b128 v[222:225], v200 offset:6976
	s_waitcnt lgkmcnt(1)
	v_mfma_f32_16x16x32_bf16 v[108:111], v[164:167], v[160:163], v[108:111]
	v_mfma_f32_16x16x32_bf16 v[104:107], v[172:175], v[160:163], v[104:107]
	v_mfma_f32_16x16x32_bf16 v[100:103], v[176:179], v[160:163], v[100:103]
	v_mfma_f32_16x16x32_bf16 v[96:99], v[184:187], v[160:163], v[96:99]
	ds_read_b128 v[160:163], v200 offset:9216
	ds_read_b128 v[226:229], v200 offset:9280
	s_waitcnt lgkmcnt(1)
	v_mfma_f32_16x16x32_bf16 v[92:95], v[164:167], v[160:163], v[92:95]
	v_mfma_f32_16x16x32_bf16 v[88:91], v[172:175], v[160:163], v[88:91]
	v_mfma_f32_16x16x32_bf16 v[80:83], v[176:179], v[160:163], v[80:83]
	v_mfma_f32_16x16x32_bf16 v[84:87], v[184:187], v[160:163], v[84:87]
	ds_read_b128 v[160:163], v200 offset:11520
	ds_read_b128 v[230:233], v200 offset:11584
	s_waitcnt lgkmcnt(1)
	v_mfma_f32_16x16x32_bf16 v[76:79], v[164:167], v[160:163], v[76:79]
	v_mfma_f32_16x16x32_bf16 v[72:75], v[172:175], v[160:163], v[72:75]
	v_mfma_f32_16x16x32_bf16 v[68:71], v[176:179], v[160:163], v[68:71]
	v_mfma_f32_16x16x32_bf16 v[64:67], v[184:187], v[160:163], v[64:67]
	ds_read_b128 v[160:163], v200 offset:13824
	ds_read_b128 v[234:237], v200 offset:13888
	s_waitcnt lgkmcnt(1)
	v_mfma_f32_16x16x32_bf16 v[60:63], v[164:167], v[160:163], v[60:63]
	v_mfma_f32_16x16x32_bf16 v[56:59], v[172:175], v[160:163], v[56:59]
	v_mfma_f32_16x16x32_bf16 v[52:55], v[176:179], v[160:163], v[52:55]
	v_mfma_f32_16x16x32_bf16 v[48:51], v[184:187], v[160:163], v[48:51]
	ds_read_b128 v[160:163], v200 offset:16128
	ds_read_b128 v[238:241], v200 offset:16192
	s_setprio 0
	s_waitcnt vmcnt(6)
	ds_write_b128 v202, v[4:7] offset:36864
	s_waitcnt vmcnt(5)
	ds_write_b128 v202, v[8:11] offset:46080
	s_waitcnt vmcnt(4)
	ds_write_b128 v202, v[12:15] offset:55296
	s_waitcnt vmcnt(3)
	ds_write_b128 v202, v[16:19] offset:64512
	v_mfma_f32_16x16x32_bf16 v[16:19], v[210:213], v[226:229], v[80:83]
	s_waitcnt vmcnt(3)
	ds_write_b128 v208, v[0:3]
	s_waitcnt vmcnt(2)
	ds_write_b128 v208, v[20:23] offset:9216
	s_waitcnt vmcnt(1)
	ds_write_b128 v208, v[24:27] offset:18432
	v_lshl_add_u64 v[80:81], s[92:93], 0, v[196:197]
	s_waitcnt vmcnt(0)
	ds_write_b128 v208, v[28:31] offset:27648
	v_mfma_f32_16x16x32_bf16 v[24:27], v[180:183], v[230:233], v[76:79]
	v_lshl_add_u64 v[82:83], s[94:95], 0, v[196:197]
	s_cselect_b32 s92, s56, s81
	s_cselect_b32 s93, s57, s82
	v_add_co_u32_e32 v76, vcc, s61, v80
	v_mfma_f32_16x16x32_bf16 v[28:31], v[192:195], v[230:233], v[72:75]
	s_nop 0
	v_addc_co_u32_e32 v77, vcc, 0, v81, vcc
	s_cselect_b32 s94, s58, s83
	v_add_co_u32_e32 v72, vcc, s62, v80
	s_waitcnt lgkmcnt(9)
	v_mfma_f32_16x16x32_bf16 v[40:43], v[164:167], v[160:163], v[40:43]
	v_addc_co_u32_e32 v73, vcc, 0, v81, vcc
	v_add_co_u32_e32 v74, vcc, s63, v80
	v_mfma_f32_16x16x32_bf16 v[36:39], v[172:175], v[160:163], v[36:39]
	s_nop 0
	v_addc_co_u32_e32 v75, vcc, 0, v81, vcc
	v_add_co_u32_e32 v78, vcc, s61, v82
	v_mfma_f32_16x16x32_bf16 v[32:35], v[176:179], v[160:163], v[32:35]
	s_nop 0
	v_addc_co_u32_e32 v79, vcc, 0, v83, vcc
	global_load_dwordx4 v[164:167], v[82:83], off
	v_mfma_f32_16x16x32_bf16 v[44:47], v[184:187], v[160:163], v[44:47]
	global_load_dwordx4 v[160:163], v[80:81], off
	v_add_co_u32_e32 v80, vcc, s62, v82
	v_mfma_f32_16x16x32_bf16 v[156:159], v[180:183], v[168:171], v[156:159]
	s_nop 0
	v_addc_co_u32_e32 v81, vcc, 0, v83, vcc
	v_add_co_u32_e32 v82, vcc, s63, v82
	v_mfma_f32_16x16x32_bf16 v[152:155], v[192:195], v[168:171], v[152:155]
	s_nop 0
	v_addc_co_u32_e32 v83, vcc, 0, v83, vcc
	s_cselect_b32 s95, s59, s84
	v_mfma_f32_16x16x32_bf16 v[148:151], v[210:213], v[168:171], v[148:151]
	s_add_u32 s58, s58, 0x100
	s_addc_u32 s59, s59, 0
	s_add_u32 s56, s56, 0x100
	v_mfma_f32_16x16x32_bf16 v[144:147], v[214:217], v[168:171], v[144:147]
	global_load_dwordx4 v[168:171], v[76:77], off
	global_load_dwordx4 v[172:175], v[72:73], off
	global_load_dwordx4 v[176:179], v[74:75], off
	s_addc_u32 s57, s57, 0
	s_cmp_gt_u32 s85, 19
	v_mfma_f32_16x16x32_bf16 v[140:143], v[180:183], v[188:191], v[140:143]
	s_mov_b32 s85, s86
	v_mfma_f32_16x16x32_bf16 v[136:139], v[192:195], v[188:191], v[136:139]
	v_mfma_f32_16x16x32_bf16 v[132:135], v[210:213], v[188:191], v[132:135]
	v_mfma_f32_16x16x32_bf16 v[128:131], v[214:217], v[188:191], v[128:131]
	v_mfma_f32_16x16x32_bf16 v[124:127], v[180:183], v[218:221], v[124:127]
	v_mfma_f32_16x16x32_bf16 v[108:111], v[180:183], v[222:225], v[108:111]
	v_mfma_f32_16x16x32_bf16 v[0:3], v[180:183], v[226:229], v[92:95]
	v_mfma_f32_16x16x32_bf16 v[60:63], v[180:183], v[234:237], v[60:63]
	s_waitcnt lgkmcnt(8)
	v_mfma_f32_16x16x32_bf16 v[40:43], v[180:183], v[238:241], v[40:43]
	global_load_dwordx4 v[180:183], v[78:79], off
	global_load_dwordx4 v[184:187], v[80:81], off
	global_load_dwordx4 v[188:191], v[82:83], off
	s_waitcnt lgkmcnt(0)
	s_barrier
	s_setprio 1
	ds_read_b128 v[72:75], v200 offset:36864
	v_mfma_f32_16x16x32_bf16 v[116:119], v[210:213], v[218:221], v[116:119]
	v_mfma_f32_16x16x32_bf16 v[112:115], v[214:217], v[218:221], v[112:115]
	v_mfma_f32_16x16x32_bf16 v[4:7], v[210:213], v[222:225], v[100:103]
	v_mfma_f32_16x16x32_bf16 v[8:11], v[214:217], v[222:225], v[96:99]
	v_mfma_f32_16x16x32_bf16 v[20:23], v[214:217], v[226:229], v[84:87]
	v_mfma_f32_16x16x32_bf16 v[68:71], v[210:213], v[230:233], v[68:71]
	v_mfma_f32_16x16x32_bf16 v[64:67], v[214:217], v[230:233], v[64:67]
	v_mfma_f32_16x16x32_bf16 v[52:55], v[210:213], v[234:237], v[52:55]
	v_mfma_f32_16x16x32_bf16 v[48:51], v[214:217], v[234:237], v[48:51]
	v_mfma_f32_16x16x32_bf16 v[32:35], v[210:213], v[238:241], v[32:35]
	ds_read_b128 v[80:83], v209
	ds_read_b128 v[210:213], v209 offset:64
	ds_read_b128 v[84:87], v200 offset:36928
	v_mfma_f32_16x16x32_bf16 v[76:79], v[214:217], v[238:241], v[44:47]
	ds_read_b128 v[92:95], v209 offset:2304
	ds_read_b128 v[214:217], v209 offset:2368
	v_mfma_f32_16x16x32_bf16 v[120:123], v[192:195], v[218:221], v[120:123]
	ds_read_b128 v[100:103], v209 offset:4608
	ds_read_b128 v[218:221], v209 offset:4672
	s_waitcnt lgkmcnt(3)
	v_mfma_f32_16x16x32_bf16 v[96:99], v[92:95], v[72:75], v[152:155]
	s_nop 2
	ds_read_b128 v[152:155], v209 offset:6912
	ds_read_b128 v[44:47], v209 offset:6976
	v_mfma_f32_16x16x32_bf16 v[104:107], v[192:195], v[222:225], v[104:107]
	v_mfma_f32_16x16x32_bf16 v[12:15], v[192:195], v[226:229], v[88:91]
	v_mfma_f32_16x16x32_bf16 v[88:91], v[80:83], v[72:75], v[156:159]
	s_waitcnt lgkmcnt(3)
	v_mfma_f32_16x16x32_bf16 v[148:151], v[100:103], v[72:75], v[148:151]
	s_waitcnt lgkmcnt(1)
	v_mfma_f32_16x16x32_bf16 v[72:75], v[152:155], v[72:75], v[144:147]
	s_nop 2
	ds_read_b128 v[144:147], v200 offset:39168
	ds_read_b128 v[222:225], v200 offset:39232
	s_waitcnt lgkmcnt(1)
	v_mfma_f32_16x16x32_bf16 v[140:143], v[80:83], v[144:147], v[140:143]
	v_mfma_f32_16x16x32_bf16 v[136:139], v[92:95], v[144:147], v[136:139]
	v_mfma_f32_16x16x32_bf16 v[132:135], v[100:103], v[144:147], v[132:135]
	v_mfma_f32_16x16x32_bf16 v[128:131], v[152:155], v[144:147], v[128:131]
	ds_read_b128 v[144:147], v200 offset:41472
	ds_read_b128 v[226:229], v200 offset:41536
	s_waitcnt lgkmcnt(1)
	v_mfma_f32_16x16x32_bf16 v[124:127], v[80:83], v[144:147], v[124:127]
	v_mfma_f32_16x16x32_bf16 v[120:123], v[92:95], v[144:147], v[120:123]
	v_mfma_f32_16x16x32_bf16 v[116:119], v[100:103], v[144:147], v[116:119]
	v_mfma_f32_16x16x32_bf16 v[112:115], v[152:155], v[144:147], v[112:115]
	ds_read_b128 v[144:147], v200 offset:43776
	ds_read_b128 v[230:233], v200 offset:43840
	v_mfma_f32_16x16x32_bf16 v[56:59], v[192:195], v[234:237], v[56:59]
	s_waitcnt lgkmcnt(1)
	v_mfma_f32_16x16x32_bf16 v[108:111], v[80:83], v[144:147], v[108:111]
	v_mfma_f32_16x16x32_bf16 v[104:107], v[92:95], v[144:147], v[104:107]
	v_mfma_f32_16x16x32_bf16 v[4:7], v[100:103], v[144:147], v[4:7]
	v_mfma_f32_16x16x32_bf16 v[8:11], v[152:155], v[144:147], v[8:11]
	ds_read_b128 v[144:147], v200 offset:46080
	ds_read_b128 v[234:237], v200 offset:46144
	v_mfma_f32_16x16x32_bf16 v[36:39], v[192:195], v[238:241], v[36:39]
	s_waitcnt lgkmcnt(1)
	v_mfma_f32_16x16x32_bf16 v[0:3], v[80:83], v[144:147], v[0:3]
	v_mfma_f32_16x16x32_bf16 v[12:15], v[92:95], v[144:147], v[12:15]
	v_mfma_f32_16x16x32_bf16 v[16:19], v[100:103], v[144:147], v[16:19]
	v_mfma_f32_16x16x32_bf16 v[20:23], v[152:155], v[144:147], v[20:23]
	ds_read_b128 v[144:147], v200 offset:48384
	ds_read_b128 v[238:241], v200 offset:48448
	s_waitcnt lgkmcnt(1)
	v_mfma_f32_16x16x32_bf16 v[24:27], v[80:83], v[144:147], v[24:27]
	v_mfma_f32_16x16x32_bf16 v[28:31], v[92:95], v[144:147], v[28:31]
	v_mfma_f32_16x16x32_bf16 v[68:71], v[100:103], v[144:147], v[68:71]
	v_mfma_f32_16x16x32_bf16 v[64:67], v[152:155], v[144:147], v[64:67]
	ds_read_b128 v[144:147], v200 offset:50688
	ds_read_b128 v[242:245], v200 offset:50752
	s_waitcnt lgkmcnt(1)
	v_mfma_f32_16x16x32_bf16 v[60:63], v[80:83], v[144:147], v[60:63]
	v_mfma_f32_16x16x32_bf16 v[56:59], v[92:95], v[144:147], v[56:59]
	v_mfma_f32_16x16x32_bf16 v[52:55], v[100:103], v[144:147], v[52:55]
	v_mfma_f32_16x16x32_bf16 v[48:51], v[152:155], v[144:147], v[48:51]
	ds_read_b128 v[144:147], v200 offset:52992
	ds_read_b128 v[192:195], v200 offset:53056
	s_waitcnt lgkmcnt(1)
	v_mfma_f32_16x16x32_bf16 v[32:35], v[100:103], v[144:147], v[32:35]
	v_mfma_f32_16x16x32_bf16 v[100:103], v[218:221], v[230:233], v[4:7]
	s_nop 2
	v_lshl_add_u64 v[4:5], s[92:93], 0, v[196:197]
	v_mfma_f32_16x16x32_bf16 v[246:249], v[152:155], v[144:147], v[76:79]
	v_lshl_add_u64 v[6:7], s[94:95], 0, v[196:197]
	v_mfma_f32_16x16x32_bf16 v[152:155], v[214:217], v[84:87], v[96:99]
	v_mfma_f32_16x16x32_bf16 v[96:99], v[44:47], v[230:233], v[8:11]
	s_nop 2
	v_add_co_u32_e32 v8, vcc, s61, v4
	v_mfma_f32_16x16x32_bf16 v[156:159], v[210:213], v[84:87], v[88:91]
	s_nop 0
	v_addc_co_u32_e32 v9, vcc, 0, v5, vcc
	v_mfma_f32_16x16x32_bf16 v[88:91], v[214:217], v[234:237], v[12:15]
	s_nop 2
	v_add_co_u32_e32 v12, vcc, s62, v4
	v_mfma_f32_16x16x32_bf16 v[40:43], v[80:83], v[144:147], v[40:43]
	s_nop 0
	v_addc_co_u32_e32 v13, vcc, 0, v5, vcc
	v_mfma_f32_16x16x32_bf16 v[80:83], v[218:221], v[234:237], v[16:19]
	s_nop 2
	v_add_co_u32_e32 v16, vcc, s63, v4
	v_mfma_f32_16x16x32_bf16 v[36:39], v[92:95], v[144:147], v[36:39]
	s_nop 0
	v_addc_co_u32_e32 v17, vcc, 0, v5, vcc
	v_mfma_f32_16x16x32_bf16 v[148:151], v[218:221], v[84:87], v[148:151]
	v_mfma_f32_16x16x32_bf16 v[144:147], v[44:47], v[84:87], v[72:75]
	v_mfma_f32_16x16x32_bf16 v[84:87], v[44:47], v[234:237], v[20:23]
	s_nop 2
	v_add_co_u32_e32 v20, vcc, s61, v6
	v_mfma_f32_16x16x32_bf16 v[76:79], v[210:213], v[238:241], v[24:27]
	s_nop 0
	v_addc_co_u32_e32 v21, vcc, 0, v7, vcc
	s_nop 0
	v_add_co_u32_e32 v24, vcc, s62, v6
	v_mfma_f32_16x16x32_bf16 v[72:75], v[214:217], v[238:241], v[28:31]
	s_nop 0
	v_addc_co_u32_e32 v25, vcc, 0, v7, vcc
	s_nop 0
	v_add_co_u32_e32 v28, vcc, s63, v6
	v_mfma_f32_16x16x32_bf16 v[92:95], v[210:213], v[234:237], v[0:3]
	s_nop 0
	v_addc_co_u32_e32 v29, vcc, 0, v7, vcc
	s_nop 0
	global_load_dwordx4 v[0:3], v[6:7], off
	s_nop 0
	global_load_dwordx4 v[4:7], v[4:5], off
	s_nop 0
	global_load_dwordx4 v[8:11], v[8:9], off
	s_nop 0
	global_load_dwordx4 v[12:15], v[12:13], off
	s_nop 0
	global_load_dwordx4 v[16:19], v[16:17], off
	s_nop 0
	global_load_dwordx4 v[20:23], v[20:21], off
	s_nop 0
	global_load_dwordx4 v[24:27], v[24:25], off
	v_mfma_f32_16x16x32_bf16 v[140:143], v[210:213], v[222:225], v[140:143]
	global_load_dwordx4 v[28:31], v[28:29], off
	s_setprio 0
	s_waitcnt vmcnt(14)
	ds_write_b128 v202, v[160:163]
	ds_write_b128 v206, v[164:167]
	s_waitcnt vmcnt(13)
	ds_write_b128 v202, v[168:171] offset:9216
	s_waitcnt vmcnt(12)
	ds_write_b128 v202, v[172:175] offset:18432
	s_waitcnt vmcnt(11)
	ds_write_b128 v202, v[176:179] offset:27648
	s_waitcnt vmcnt(10)
	ds_write_b128 v206, v[180:183] offset:9216
	s_waitcnt vmcnt(9)
	ds_write_b128 v206, v[184:187] offset:18432
	s_waitcnt vmcnt(8)
	ds_write_b128 v206, v[188:191] offset:27648
	s_waitcnt lgkmcnt(0)
	v_mfma_f32_16x16x32_bf16 v[136:139], v[214:217], v[222:225], v[136:139]
	s_barrier
	s_setprio 1
	v_mfma_f32_16x16x32_bf16 v[132:135], v[218:221], v[222:225], v[132:135]
	v_mfma_f32_16x16x32_bf16 v[128:131], v[44:47], v[222:225], v[128:131]
	v_mfma_f32_16x16x32_bf16 v[124:127], v[210:213], v[226:229], v[124:127]
	v_mfma_f32_16x16x32_bf16 v[120:123], v[214:217], v[226:229], v[120:123]
	v_mfma_f32_16x16x32_bf16 v[116:119], v[218:221], v[226:229], v[116:119]
	v_mfma_f32_16x16x32_bf16 v[112:115], v[44:47], v[226:229], v[112:115]
	v_mfma_f32_16x16x32_bf16 v[108:111], v[210:213], v[230:233], v[108:111]
	v_mfma_f32_16x16x32_bf16 v[104:107], v[214:217], v[230:233], v[104:107]
	v_mfma_f32_16x16x32_bf16 v[68:71], v[218:221], v[238:241], v[68:71]
	v_mfma_f32_16x16x32_bf16 v[64:67], v[44:47], v[238:241], v[64:67]
	v_mfma_f32_16x16x32_bf16 v[60:63], v[210:213], v[242:245], v[60:63]
	v_mfma_f32_16x16x32_bf16 v[56:59], v[214:217], v[242:245], v[56:59]
	v_mfma_f32_16x16x32_bf16 v[52:55], v[218:221], v[242:245], v[52:55]
	v_mfma_f32_16x16x32_bf16 v[48:51], v[44:47], v[242:245], v[48:51]
	v_mfma_f32_16x16x32_bf16 v[40:43], v[210:213], v[192:195], v[40:43]
	v_mfma_f32_16x16x32_bf16 v[36:39], v[214:217], v[192:195], v[36:39]
	v_mfma_f32_16x16x32_bf16 v[32:35], v[218:221], v[192:195], v[32:35]
	v_mfma_f32_16x16x32_bf16 v[44:47], v[44:47], v[192:195], v[246:249]
	s_cbranch_scc0 .LBB0_1511
	s_cmp_eq_u32 s78, 0
	s_mov_b32 s99, 0x6a44000
	s_cselect_b32 s99, s99, 0x7a44000
	s_lshl_b32 s98, s80, 11
	s_lshl_b32 s100, s79, 1
	s_add_u32 s98, s98, s100
	s_add_u32 s98, s98, s99
	s_add_u32 s100, s34, s98
	s_addc_u32 s101, s35, 0
	v_and_b32_e32 v160, 15, v207
	v_and_b32_e32 v161, 0x80, v203
	v_add_u32_e32 v160, v160, v161
	v_lshlrev_b32_e32 v160, 11, v160
	v_and_b32_e32 v161, 0xc0, v207
	v_lshl_add_u32 v160, v161, 1, v160
	v_and_b32_e32 v161, 4, v203
	v_lshl_add_u32 v160, v161, 3, v160
	v_and_b32_e32 v161, 8, v203
	v_lshl_add_u32 v160, v161, 1, v160
	v_cvt_pk_bf16_f32 v156, v156, v157
	v_cvt_pk_bf16_f32 v157, v158, v159
	v_cvt_pk_bf16_f32 v158, v152, v153
	v_cvt_pk_bf16_f32 v159, v154, v155
	v_cvt_pk_bf16_f32 v148, v148, v149
	v_cvt_pk_bf16_f32 v149, v150, v151
	v_cvt_pk_bf16_f32 v150, v144, v145
	v_cvt_pk_bf16_f32 v151, v146, v147
	v_permlane16_swap_b32_e32 v156, v158
	v_permlane16_swap_b32_e32 v157, v159
	v_permlane16_swap_b32_e32 v148, v150
	v_permlane16_swap_b32_e32 v149, v151
	global_store_dwordx4 v160, v[156:159], s[100:101] sc1
	global_store_dwordx4 v160, v[148:151], s[100:101] offset:64 sc1
	s_add_u32 s100, s100, 0x8000
	s_addc_u32 s101, s101, 0
	v_cvt_pk_bf16_f32 v140, v140, v141
	v_cvt_pk_bf16_f32 v141, v142, v143
	v_cvt_pk_bf16_f32 v142, v136, v137
	v_cvt_pk_bf16_f32 v143, v138, v139
	v_cvt_pk_bf16_f32 v132, v132, v133
	v_cvt_pk_bf16_f32 v133, v134, v135
	v_cvt_pk_bf16_f32 v134, v128, v129
	v_cvt_pk_bf16_f32 v135, v130, v131
	v_permlane16_swap_b32_e32 v140, v142
	v_permlane16_swap_b32_e32 v141, v143
	v_permlane16_swap_b32_e32 v132, v134
	v_permlane16_swap_b32_e32 v133, v135
	global_store_dwordx4 v160, v[140:143], s[100:101] sc1
	global_store_dwordx4 v160, v[132:135], s[100:101] offset:64 sc1
	s_add_u32 s100, s100, 0x8000
	s_addc_u32 s101, s101, 0
	v_cvt_pk_bf16_f32 v124, v124, v125
	v_cvt_pk_bf16_f32 v125, v126, v127
	v_cvt_pk_bf16_f32 v126, v120, v121
	v_cvt_pk_bf16_f32 v127, v122, v123
	v_cvt_pk_bf16_f32 v116, v116, v117
	v_cvt_pk_bf16_f32 v117, v118, v119
	v_cvt_pk_bf16_f32 v118, v112, v113
	v_cvt_pk_bf16_f32 v119, v114, v115
	v_permlane16_swap_b32_e32 v124, v126
	v_permlane16_swap_b32_e32 v125, v127
	v_permlane16_swap_b32_e32 v116, v118
	v_permlane16_swap_b32_e32 v117, v119
	global_store_dwordx4 v160, v[124:127], s[100:101] sc1
	global_store_dwordx4 v160, v[116:119], s[100:101] offset:64 sc1
	s_add_u32 s100, s100, 0x8000
	s_addc_u32 s101, s101, 0
	v_cvt_pk_bf16_f32 v108, v108, v109
	v_cvt_pk_bf16_f32 v109, v110, v111
	v_cvt_pk_bf16_f32 v110, v104, v105
	v_cvt_pk_bf16_f32 v111, v106, v107
	v_cvt_pk_bf16_f32 v100, v100, v101
	v_cvt_pk_bf16_f32 v101, v102, v103
	v_cvt_pk_bf16_f32 v102, v96, v97
	v_cvt_pk_bf16_f32 v103, v98, v99
	v_permlane16_swap_b32_e32 v108, v110
	v_permlane16_swap_b32_e32 v109, v111
	v_permlane16_swap_b32_e32 v100, v102
	v_permlane16_swap_b32_e32 v101, v103
	global_store_dwordx4 v160, v[108:111], s[100:101] sc1
	global_store_dwordx4 v160, v[100:103], s[100:101] offset:64 sc1
	s_add_u32 s100, s100, 0x8000
	s_addc_u32 s101, s101, 0
	v_cvt_pk_bf16_f32 v92, v92, v93
	v_cvt_pk_bf16_f32 v93, v94, v95
	v_cvt_pk_bf16_f32 v94, v88, v89
	v_cvt_pk_bf16_f32 v95, v90, v91
	v_cvt_pk_bf16_f32 v80, v80, v81
	v_cvt_pk_bf16_f32 v81, v82, v83
	v_cvt_pk_bf16_f32 v82, v84, v85
	v_cvt_pk_bf16_f32 v83, v86, v87
	v_permlane16_swap_b32_e32 v92, v94
	v_permlane16_swap_b32_e32 v93, v95
	v_permlane16_swap_b32_e32 v80, v82
	v_permlane16_swap_b32_e32 v81, v83
	global_store_dwordx4 v160, v[92:95], s[100:101] sc1
	global_store_dwordx4 v160, v[80:83], s[100:101] offset:64 sc1
	s_add_u32 s100, s100, 0x8000
	s_addc_u32 s101, s101, 0
	v_cvt_pk_bf16_f32 v76, v76, v77
	v_cvt_pk_bf16_f32 v77, v78, v79
	v_cvt_pk_bf16_f32 v78, v72, v73
	v_cvt_pk_bf16_f32 v79, v74, v75
	v_cvt_pk_bf16_f32 v68, v68, v69
	v_cvt_pk_bf16_f32 v69, v70, v71
	v_cvt_pk_bf16_f32 v70, v64, v65
	v_cvt_pk_bf16_f32 v71, v66, v67
	v_permlane16_swap_b32_e32 v76, v78
	v_permlane16_swap_b32_e32 v77, v79
	v_permlane16_swap_b32_e32 v68, v70
	v_permlane16_swap_b32_e32 v69, v71
	global_store_dwordx4 v160, v[76:79], s[100:101] sc1
	global_store_dwordx4 v160, v[68:71], s[100:101] offset:64 sc1
	s_add_u32 s100, s100, 0x8000
	s_addc_u32 s101, s101, 0
	v_cvt_pk_bf16_f32 v60, v60, v61
	v_cvt_pk_bf16_f32 v61, v62, v63
	v_cvt_pk_bf16_f32 v62, v56, v57
	v_cvt_pk_bf16_f32 v63, v58, v59
	v_cvt_pk_bf16_f32 v52, v52, v53
	v_cvt_pk_bf16_f32 v53, v54, v55
	v_cvt_pk_bf16_f32 v54, v48, v49
	v_cvt_pk_bf16_f32 v55, v50, v51
	v_permlane16_swap_b32_e32 v60, v62
	v_permlane16_swap_b32_e32 v61, v63
	v_permlane16_swap_b32_e32 v52, v54
	v_permlane16_swap_b32_e32 v53, v55
	global_store_dwordx4 v160, v[60:63], s[100:101] sc1
	global_store_dwordx4 v160, v[52:55], s[100:101] offset:64 sc1
	s_add_u32 s100, s100, 0x8000
	s_addc_u32 s101, s101, 0
	v_cvt_pk_bf16_f32 v40, v40, v41
	v_cvt_pk_bf16_f32 v41, v42, v43
	v_cvt_pk_bf16_f32 v42, v36, v37
	v_cvt_pk_bf16_f32 v43, v38, v39
	v_cvt_pk_bf16_f32 v32, v32, v33
	v_cvt_pk_bf16_f32 v33, v34, v35
	v_cvt_pk_bf16_f32 v34, v44, v45
	v_cvt_pk_bf16_f32 v35, v46, v47
	v_permlane16_swap_b32_e32 v40, v42
	v_permlane16_swap_b32_e32 v41, v43
	v_permlane16_swap_b32_e32 v32, v34
	v_permlane16_swap_b32_e32 v33, v35
	global_store_dwordx4 v160, v[40:43], s[100:101] sc1
	global_store_dwordx4 v160, v[32:35], s[100:101] offset:64 sc1
	s_and_b64 vcc, exec, s[54:55]
	s_mov_b32 s78, s77
	s_mov_b32 s79, s76
	s_mov_b32 s80, s75
	s_mov_b64 s[58:59], s[52:53]
	s_mov_b64 s[56:57], s[50:51]
	s_cbranch_vccz .LBB0_1508
	s_load_dwordx4 s[84:87], s[0:1], 0x100
	s_mov_b64 s[92:93], s[96:97]
